# GEMM mainloops: removed the 48 per-segment s_setprio flips, one static s_setprio 1 for waves 4-7 before each K loop, reset to 0 at loop exit
# speedup vs baseline: 1.0131x; 1.0131x over previous
; #define PG8_STAGE(bufoff, gbase, voff) do { _Pragma("unroll") for (int _i = 0; _i < 2; ++_i) \
;         __builtin_amdgcn_global_load_lds((const unsigned*)((const char*)(gbase) + (voff)[_i]), (LAS unsigned*)(lds + (bufoff) + ldsw + _i * 8192), 16, 0, 0); } while (0)
; #define PG8_LDA(dst, b, h) do { _Pragma("unroll") for (int m = 0; m < 4; ++m) _Pragma("unroll") for (int k = 0; k < 2; ++k) dst[m][k] = *(const LAS bf16x8*)(lds + PG8_SA(b, h) + aoff + m * 2048 + k * 1024); } while (0)
; #define PG8_LDB(dst, b, h) do { _Pragma("unroll") for (int n = 0; n < 2; ++n) _Pragma("unroll") for (int k = 0; k < 2; ++k) dst[n][k] = *(const LAS bf16x8*)(lds + PG8_SB(b, h) + boff + n * 2048 + k * 1024); } while (0)
; #define PG8_MMA(ai, bj, At, Bt) do { __builtin_amdgcn_s_setprio(1); _Pragma("unroll") for (int m = 0; m < 4; ++m) _Pragma("unroll") for (int n = 0; n < 2; ++n) _Pragma("unroll") for (int k = 0; k < 2; ++k) \
;         acc[ai][bj][m][n] = __builtin_amdgcn_mfma_f32_16x16x32_bf16(Bt[n][k], At[m][k], acc[ai][bj][m][n], 0, 0, 0); __builtin_amdgcn_s_setprio(0); } while (0)
; #define PG8_WAIT_V(n) asm volatile("s_waitcnt vmcnt(" #n ")" ::: "memory")
; #define PG8_WAIT_L(n) asm volatile("s_waitcnt lgkmcnt(" #n ")" ::: "memory")
; #define PG8_BAR __builtin_amdgcn_s_barrier()
; #define PG8_SCHED __builtin_amdgcn_sched_barrier(0)
; template <class Epi>
; DI void gemm_phase(ldsp lds, const Gemm g, const StaticOrder S, const Epi E) {
;     ...
;         for (int t = 0; t < nt; t += 2) {
;             const bool last = (t == nt - 2);
;             const char* a1 = cA + (size_t)(t + 1) * kstep;
;             const char* a2 = last ? nA : cA + (size_t)(t + 2) * kstep; const char* b2 = last ? nB : cB + (size_t)(t + 2) * kstep;
;             const char* a3 = a2 + kstep; const char* b3 = b2 + kstep;
;             PG8_LDB(B0, 0, 0); PG8_LDB(B1, 0, 1); PG8_SCHED; PG8_LDA(At, 0, 0); PG8_STAGE(PG8_SA(1, 1), a1 + hstepA, voffA);
;             PG8_WAIT_V(8); PG8_WAIT_L(0); PG8_BAR; PG8_MMA(0, 0, At, B0); PG8_MMA(0, 1, At, B1); PG8_BAR; PG8_SCHED;
;     ...
;         for (int a = 0; a < 2; ++a)
; #pragma unroll
;             for (int b = 0; b < 2; ++b)
; #pragma unroll
;                 for (int m = 0; m < 4; ++m)
; #pragma unroll
;                     for (int n = 0; n < 2; ++n) acc[a][b][m][n] = (f32x4){0.f, 0.f, 0.f, 0.f};
.LBB0_186:
	s_ashr_i32 s11, s10, 31
	s_lshl_b64 s[12:13], s[10:11], 19
	s_add_u32 s12, s25, s12
	s_addc_u32 s13, s26, s13
	s_and_b64 s[14:15], s[0:1], exec
	s_cselect_b32 s11, s13, s19
	s_cselect_b32 s40, s12, s18
	s_ashr_i32 s9, s8, 31
	s_lshl_b64 s[14:15], s[8:9], 19
	s_add_u32 s14, s27, s14
	s_addc_u32 s15, s29, s15
	s_and_b64 s[22:23], s[0:1], exec
	s_cselect_b32 s9, s15, s21
	s_cselect_b32 s41, s14, s20
	s_add_u32 s18, s18, 0x40080
	s_addc_u32 s19, s19, 0
	s_add_u32 s42, s20, 0x100
	v_mov_b32_e32 v2, 0
	s_addc_u32 s43, s21, 0
	s_mov_b32 s44, -2
	v_mov_b32_e32 v3, v2
	v_mov_b32_e32 v4, v2
	v_mov_b32_e32 v5, v2
	v_mov_b32_e32 v6, v2
	v_mov_b32_e32 v7, v2
	v_mov_b32_e32 v8, v2
	v_mov_b32_e32 v9, v2
	v_mov_b32_e32 v18, v2
	v_mov_b32_e32 v19, v2
	v_mov_b32_e32 v20, v2
	v_mov_b32_e32 v21, v2
	v_mov_b32_e32 v22, v2
	v_mov_b32_e32 v23, v2
	v_mov_b32_e32 v24, v2
	v_mov_b32_e32 v25, v2
	v_mov_b32_e32 v34, v2
	v_mov_b32_e32 v35, v2
	v_mov_b32_e32 v36, v2
	v_mov_b32_e32 v37, v2
	v_mov_b32_e32 v38, v2
	v_mov_b32_e32 v39, v2
	v_mov_b32_e32 v40, v2
	v_mov_b32_e32 v41, v2
	v_mov_b32_e32 v50, v2
	v_mov_b32_e32 v51, v2
	v_mov_b32_e32 v52, v2
	v_mov_b32_e32 v53, v2
	v_mov_b32_e32 v54, v2
	v_mov_b32_e32 v55, v2
	v_mov_b32_e32 v56, v2
	v_mov_b32_e32 v57, v2
	v_mov_b32_e32 v10, v2
	v_mov_b32_e32 v11, v2
	v_mov_b32_e32 v12, v2
	v_mov_b32_e32 v13, v2
	v_mov_b32_e32 v14, v2
	v_mov_b32_e32 v15, v2
	v_mov_b32_e32 v16, v2
	v_mov_b32_e32 v17, v2
	v_mov_b32_e32 v26, v2
	v_mov_b32_e32 v27, v2
	v_mov_b32_e32 v28, v2
	v_mov_b32_e32 v29, v2
	v_mov_b32_e32 v30, v2
	v_mov_b32_e32 v31, v2
	v_mov_b32_e32 v32, v2
	v_mov_b32_e32 v33, v2
	v_mov_b32_e32 v42, v2
	v_mov_b32_e32 v43, v2
	v_mov_b32_e32 v44, v2
	v_mov_b32_e32 v45, v2
	v_mov_b32_e32 v46, v2
	v_mov_b32_e32 v47, v2
	v_mov_b32_e32 v48, v2
	v_mov_b32_e32 v49, v2
	v_mov_b32_e32 v58, v2
	v_mov_b32_e32 v59, v2
	v_mov_b32_e32 v60, v2
	v_mov_b32_e32 v61, v2
	v_mov_b32_e32 v62, v2
	v_mov_b32_e32 v63, v2
	v_mov_b32_e32 v64, v2
	v_mov_b32_e32 v65, v2
	v_mov_b32_e32 v66, v2
	v_mov_b32_e32 v67, v2
	v_mov_b32_e32 v68, v2
	v_mov_b32_e32 v69, v2
	v_mov_b32_e32 v70, v2
	v_mov_b32_e32 v71, v2
	v_mov_b32_e32 v72, v2
	v_mov_b32_e32 v73, v2
	v_mov_b32_e32 v82, v2
	v_mov_b32_e32 v83, v2
	v_mov_b32_e32 v84, v2
	v_mov_b32_e32 v85, v2
	v_mov_b32_e32 v86, v2
	v_mov_b32_e32 v87, v2
	v_mov_b32_e32 v88, v2
	v_mov_b32_e32 v89, v2
	v_mov_b32_e32 v98, v2
	v_mov_b32_e32 v99, v2
	v_mov_b32_e32 v100, v2
	v_mov_b32_e32 v101, v2
	v_mov_b32_e32 v102, v2
	v_mov_b32_e32 v103, v2
	v_mov_b32_e32 v104, v2
	v_mov_b32_e32 v105, v2
	v_mov_b32_e32 v114, v2
	v_mov_b32_e32 v115, v2
	v_mov_b32_e32 v116, v2
	v_mov_b32_e32 v117, v2
	v_mov_b32_e32 v118, v2
	v_mov_b32_e32 v119, v2
	v_mov_b32_e32 v120, v2
	v_mov_b32_e32 v121, v2
	v_mov_b32_e32 v74, v2
	v_mov_b32_e32 v75, v2
	v_mov_b32_e32 v76, v2
	v_mov_b32_e32 v77, v2
	v_mov_b32_e32 v78, v2
	v_mov_b32_e32 v79, v2
	v_mov_b32_e32 v80, v2
	v_mov_b32_e32 v81, v2
	v_mov_b32_e32 v90, v2
	v_mov_b32_e32 v91, v2
	v_mov_b32_e32 v92, v2
	v_mov_b32_e32 v93, v2
	v_mov_b32_e32 v94, v2
	v_mov_b32_e32 v95, v2
	v_mov_b32_e32 v96, v2
	v_mov_b32_e32 v97, v2
	v_mov_b32_e32 v106, v2
	v_mov_b32_e32 v107, v2
	v_mov_b32_e32 v108, v2
	v_mov_b32_e32 v109, v2
	v_mov_b32_e32 v110, v2
	v_mov_b32_e32 v111, v2
	v_mov_b32_e32 v112, v2
	v_mov_b32_e32 v113, v2
	v_mov_b32_e32 v122, v2
	v_mov_b32_e32 v123, v2
	v_mov_b32_e32 v124, v2
	v_mov_b32_e32 v125, v2
	v_mov_b32_e32 v126, v2
	v_mov_b32_e32 v127, v2
	v_mov_b32_e32 v128, v2
	v_mov_b32_e32 v129, v2
	v_readfirstlane_b32 s32, v153
	s_nop 3
	s_lshr_b32 s32, s32, 6
	s_cmp_ge_u32 s32, 4
	s_cbranch_scc0 .Lgemm_prio_skip1
	s_setprio 1
.Lgemm_prio_skip1:
.LBB0_187:
	s_add_u32 s20, s18, 0xfffc0080
	s_addc_u32 s21, s19, -1
	s_add_i32 s45, 0, 0x10000
	s_cmp_eq_u32 s44, 12
	s_cselect_b32 s23, s11, s21
	s_cselect_b32 s22, s40, s20
	v_add_u32_e32 v140, s45, v143
	s_cselect_b32 s21, s9, s43
	s_cselect_b32 s20, s41, s42
	s_add_i32 s48, 0, 0x14000
	ds_read_b128 v[146:149], v140
	ds_read_b128 v[156:159], v140 offset:1024
	ds_read_b128 v[160:163], v140 offset:2048
	ds_read_b128 v[164:167], v140 offset:3072
	v_add_u32_e32 v140, s48, v143
	ds_read_b128 v[168:171], v140
	ds_read_b128 v[172:175], v140 offset:1024
	ds_read_b128 v[176:179], v140 offset:2048
	ds_read_b128 v[180:183], v140 offset:3072
	v_lshl_add_u64 v[140:141], s[18:19], 0, v[136:137]
	s_add_i32 m0, s17, 0xc000
	ds_read_b128 v[184:187], v145
	ds_read_b128 v[188:191], v145 offset:1024
	ds_read_b128 v[192:195], v145 offset:2048
	ds_read_b128 v[196:199], v145 offset:3072
	ds_read_b128 v[218:221], v145 offset:4096
	ds_read_b128 v[222:225], v145 offset:5120
	ds_read_b128 v[226:229], v145 offset:6144
	ds_read_b128 v[230:233], v145 offset:7168
	global_load_lds_dwordx4 v[140:141], off
	v_lshl_add_u64 v[140:141], s[18:19], 0, v[138:139]
	s_add_i32 m0, s17, 0xe000
	s_nop 0
	global_load_lds_dwordx4 v[140:141], off
	s_waitcnt vmcnt(8)
	s_waitcnt lgkmcnt(0)
	s_barrier
; #define PG8_STAGE(bufoff, gbase, voff) do { _Pragma("unroll") for (int _i = 0; _i < 2; ++_i) \
;         __builtin_amdgcn_global_load_lds((const unsigned*)((const char*)(gbase) + (voff)[_i]), (LAS unsigned*)(lds + (bufoff) + ldsw + _i * 8192), 16, 0, 0); } while (0)
; #define PG8_LDA(dst, b, h) do { _Pragma("unroll") for (int m = 0; m < 4; ++m) _Pragma("unroll") for (int k = 0; k < 2; ++k) dst[m][k] = *(const LAS bf16x8*)(lds + PG8_SA(b, h) + aoff + m * 2048 + k * 1024); } while (0)
; #define PG8_MMA(ai, bj, At, Bt) do { __builtin_amdgcn_s_setprio(1); _Pragma("unroll") for (int m = 0; m < 4; ++m) _Pragma("unroll") for (int n = 0; n < 2; ++n) _Pragma("unroll") for (int k = 0; k < 2; ++k) \
;         acc[ai][bj][m][n] = __builtin_amdgcn_mfma_f32_16x16x32_bf16(Bt[n][k], At[m][k], acc[ai][bj][m][n], 0, 0, 0); __builtin_amdgcn_s_setprio(0); } while (0)
; #define PG8_WAIT_V(n) asm volatile("s_waitcnt vmcnt(" #n ")" ::: "memory")
; #define PG8_WAIT_L(n) asm volatile("s_waitcnt lgkmcnt(" #n ")" ::: "memory")
; #define PG8_BAR __builtin_amdgcn_s_barrier()
; #define PG8_SCHED __builtin_amdgcn_sched_barrier(0)
; template <class Epi>
; DI void gemm_phase(ldsp lds, const Gemm g, const StaticOrder S, const Epi E) {
;     ...
;             PG8_WAIT_V(8); PG8_WAIT_L(0); PG8_BAR; PG8_MMA(0, 0, At, B0); PG8_MMA(0, 1, At, B1); PG8_BAR; PG8_SCHED;
;             PG8_LDA(At, 0, 1); PG8_STAGE(PG8_SB(0, 0), b2, voffB); PG8_STAGE(PG8_SB(0, 1), b2 + hstepB, voffB); PG8_STAGE(PG8_SA(0, 0), a2, voffA);
;             PG8_WAIT_V(8); PG8_WAIT_L(0); PG8_BAR; PG8_MMA(1, 0, At, B0); PG8_MMA(1, 1, At, B1); PG8_BAR; PG8_SCHED;
	s_waitcnt lgkmcnt(0)
	v_mfma_f32_16x16x32_bf16 v[126:129], v[146:149], v[184:187], v[126:129]
	v_mfma_f32_16x16x32_bf16 v[122:125], v[160:163], v[184:187], v[122:125]
	v_mfma_f32_16x16x32_bf16 v[110:113], v[146:149], v[192:195], v[110:113]
	v_mfma_f32_16x16x32_bf16 v[106:109], v[160:163], v[192:195], v[106:109]
	v_mfma_f32_16x16x32_bf16 v[94:97], v[146:149], v[218:221], v[94:97]
	v_mfma_f32_16x16x32_bf16 v[90:93], v[160:163], v[218:221], v[90:93]
	v_mfma_f32_16x16x32_bf16 v[78:81], v[146:149], v[226:229], v[78:81]
	v_mfma_f32_16x16x32_bf16 v[74:77], v[160:163], v[226:229], v[74:77]
	v_mfma_f32_16x16x32_bf16 v[126:129], v[156:159], v[188:191], v[126:129]
	v_mfma_f32_16x16x32_bf16 v[122:125], v[164:167], v[188:191], v[122:125]
	v_mfma_f32_16x16x32_bf16 v[110:113], v[156:159], v[196:199], v[110:113]
	v_mfma_f32_16x16x32_bf16 v[106:109], v[164:167], v[196:199], v[106:109]
	v_mfma_f32_16x16x32_bf16 v[94:97], v[156:159], v[222:225], v[94:97]
	v_mfma_f32_16x16x32_bf16 v[90:93], v[164:167], v[222:225], v[90:93]
	v_mfma_f32_16x16x32_bf16 v[78:81], v[156:159], v[230:233], v[78:81]
	v_mfma_f32_16x16x32_bf16 v[74:77], v[164:167], v[230:233], v[74:77]
	v_mfma_f32_16x16x32_bf16 v[118:121], v[168:171], v[184:187], v[118:121]
	v_mfma_f32_16x16x32_bf16 v[114:117], v[176:179], v[184:187], v[114:117]
	v_mfma_f32_16x16x32_bf16 v[102:105], v[168:171], v[192:195], v[102:105]
	v_mfma_f32_16x16x32_bf16 v[98:101], v[176:179], v[192:195], v[98:101]
	v_mfma_f32_16x16x32_bf16 v[86:89], v[168:171], v[218:221], v[86:89]
	v_mfma_f32_16x16x32_bf16 v[82:85], v[176:179], v[218:221], v[82:85]
	v_mfma_f32_16x16x32_bf16 v[70:73], v[168:171], v[226:229], v[70:73]
	v_mfma_f32_16x16x32_bf16 v[66:69], v[176:179], v[226:229], v[66:69]
	v_mfma_f32_16x16x32_bf16 v[118:121], v[172:175], v[188:191], v[118:121]
	v_mfma_f32_16x16x32_bf16 v[114:117], v[180:183], v[188:191], v[114:117]
	v_mfma_f32_16x16x32_bf16 v[102:105], v[172:175], v[196:199], v[102:105]
	v_mfma_f32_16x16x32_bf16 v[98:101], v[180:183], v[196:199], v[98:101]
	v_mfma_f32_16x16x32_bf16 v[86:89], v[172:175], v[222:225], v[86:89]
	v_mfma_f32_16x16x32_bf16 v[82:85], v[180:183], v[222:225], v[82:85]
	v_mfma_f32_16x16x32_bf16 v[70:73], v[172:175], v[230:233], v[70:73]
	v_mfma_f32_16x16x32_bf16 v[66:69], v[180:183], v[230:233], v[66:69]
	s_barrier
	s_add_i32 s45, s45, s31
	v_lshl_add_u64 v[140:141], s[20:21], 0, v[0:1]
	s_mov_b32 m0, s45
	ds_read_b128 v[184:187], v145 offset:16384
	ds_read_b128 v[188:191], v145 offset:17408
	ds_read_b128 v[192:195], v145 offset:18432
	ds_read_b128 v[196:199], v145 offset:19456
	ds_read_b128 v[218:221], v145 offset:20480
	ds_read_b128 v[222:225], v145 offset:21504
	ds_read_b128 v[226:229], v145 offset:22528
	ds_read_b128 v[230:233], v145 offset:23552
	global_load_lds_dwordx4 v[140:141], off
	s_add_i32 m0, s45, 0x2000
	s_add_u32 s46, s20, 0x40000
	v_lshl_add_u64 v[150:151], s[20:21], 0, v[130:131]
	s_addc_u32 s47, s21, 0
	s_add_i32 s45, s48, s31
	global_load_lds_dwordx4 v[150:151], off
	v_lshl_add_u64 v[206:207], s[46:47], 0, v[0:1]
	s_mov_b32 m0, s45
	v_lshl_add_u64 v[208:209], s[22:23], 0, v[132:133]
	global_load_lds_dwordx4 v[206:207], off
	v_lshl_add_u64 v[206:207], s[46:47], 0, v[130:131]
	s_add_i32 m0, s45, 0x2000
	s_nop 0
	global_load_lds_dwordx4 v[206:207], off
	v_lshl_add_u64 v[206:207], s[22:23], 0, v[134:135]
	s_mov_b32 m0, s17
	s_nop 0
	global_load_lds_dwordx4 v[206:207], off
	s_mov_b32 m0, s33
	s_nop 0
	global_load_lds_dwordx4 v[208:209], off
	s_waitcnt vmcnt(8)
	s_waitcnt lgkmcnt(0)
	s_barrier
	s_waitcnt lgkmcnt(0)
	v_mfma_f32_16x16x32_bf16 v[62:65], v[146:149], v[184:187], v[62:65]
	v_mfma_f32_16x16x32_bf16 v[58:61], v[160:163], v[184:187], v[58:61]
	v_mfma_f32_16x16x32_bf16 v[46:49], v[146:149], v[192:195], v[46:49]
	v_mfma_f32_16x16x32_bf16 v[42:45], v[160:163], v[192:195], v[42:45]
	v_mfma_f32_16x16x32_bf16 v[30:33], v[146:149], v[218:221], v[30:33]
	v_mfma_f32_16x16x32_bf16 v[26:29], v[160:163], v[218:221], v[26:29]
	v_mfma_f32_16x16x32_bf16 v[14:17], v[146:149], v[226:229], v[14:17]
	v_mfma_f32_16x16x32_bf16 v[10:13], v[160:163], v[226:229], v[10:13]
	v_mfma_f32_16x16x32_bf16 v[62:65], v[156:159], v[188:191], v[62:65]
	v_mfma_f32_16x16x32_bf16 v[58:61], v[164:167], v[188:191], v[58:61]
	v_mfma_f32_16x16x32_bf16 v[46:49], v[156:159], v[196:199], v[46:49]
	v_mfma_f32_16x16x32_bf16 v[42:45], v[164:167], v[196:199], v[42:45]
	v_mfma_f32_16x16x32_bf16 v[30:33], v[156:159], v[222:225], v[30:33]
	v_mfma_f32_16x16x32_bf16 v[26:29], v[164:167], v[222:225], v[26:29]
	v_mfma_f32_16x16x32_bf16 v[14:17], v[156:159], v[230:233], v[14:17]
	v_mfma_f32_16x16x32_bf16 v[10:13], v[164:167], v[230:233], v[10:13]
	v_mfma_f32_16x16x32_bf16 v[54:57], v[168:171], v[184:187], v[54:57]
	v_mfma_f32_16x16x32_bf16 v[50:53], v[176:179], v[184:187], v[50:53]
	v_mfma_f32_16x16x32_bf16 v[38:41], v[168:171], v[192:195], v[38:41]
	v_mfma_f32_16x16x32_bf16 v[34:37], v[176:179], v[192:195], v[34:37]
	v_mfma_f32_16x16x32_bf16 v[22:25], v[168:171], v[218:221], v[22:25]
	v_mfma_f32_16x16x32_bf16 v[18:21], v[176:179], v[218:221], v[18:21]
	v_mfma_f32_16x16x32_bf16 v[6:9], v[168:171], v[226:229], v[6:9]
	v_mfma_f32_16x16x32_bf16 v[2:5], v[176:179], v[226:229], v[2:5]
	v_mfma_f32_16x16x32_bf16 v[54:57], v[172:175], v[188:191], v[54:57]
	v_mfma_f32_16x16x32_bf16 v[50:53], v[180:183], v[188:191], v[50:53]
	v_mfma_f32_16x16x32_bf16 v[38:41], v[172:175], v[196:199], v[38:41]
	v_mfma_f32_16x16x32_bf16 v[34:37], v[180:183], v[196:199], v[34:37]
	v_mfma_f32_16x16x32_bf16 v[22:25], v[172:175], v[222:225], v[22:25]
	v_mfma_f32_16x16x32_bf16 v[18:21], v[180:183], v[222:225], v[18:21]
	v_mfma_f32_16x16x32_bf16 v[6:9], v[172:175], v[230:233], v[6:9]
	v_mfma_f32_16x16x32_bf16 v[2:5], v[180:183], v[230:233], v[2:5]
	s_barrier
; #define PG8_STAGE(bufoff, gbase, voff) do { _Pragma("unroll") for (int _i = 0; _i < 2; ++_i) \
;         __builtin_amdgcn_global_load_lds((const unsigned*)((const char*)(gbase) + (voff)[_i]), (LAS unsigned*)(lds + (bufoff) + ldsw + _i * 8192), 16, 0, 0); } while (0)
; #define PG8_LDA(dst, b, h) do { _Pragma("unroll") for (int m = 0; m < 4; ++m) _Pragma("unroll") for (int k = 0; k < 2; ++k) dst[m][k] = *(const LAS bf16x8*)(lds + PG8_SA(b, h) + aoff + m * 2048 + k * 1024); } while (0)
; #define PG8_LDB(dst, b, h) do { _Pragma("unroll") for (int n = 0; n < 2; ++n) _Pragma("unroll") for (int k = 0; k < 2; ++k) dst[n][k] = *(const LAS bf16x8*)(lds + PG8_SB(b, h) + boff + n * 2048 + k * 1024); } while (0)
; #define PG8_MMA(ai, bj, At, Bt) do { __builtin_amdgcn_s_setprio(1); _Pragma("unroll") for (int m = 0; m < 4; ++m) _Pragma("unroll") for (int n = 0; n < 2; ++n) _Pragma("unroll") for (int k = 0; k < 2; ++k) \
;         acc[ai][bj][m][n] = __builtin_amdgcn_mfma_f32_16x16x32_bf16(Bt[n][k], At[m][k], acc[ai][bj][m][n], 0, 0, 0); __builtin_amdgcn_s_setprio(0); } while (0)
; #define PG8_WAIT_V(n) asm volatile("s_waitcnt vmcnt(" #n ")" ::: "memory")
; #define PG8_WAIT_L(n) asm volatile("s_waitcnt lgkmcnt(" #n ")" ::: "memory")
; #define PG8_BAR __builtin_amdgcn_s_barrier()
; #define PG8_SCHED __builtin_amdgcn_sched_barrier(0)
; template <class Epi>
; DI void gemm_phase(ldsp lds, const Gemm g, const StaticOrder S, const Epi E) {
;     ...
;             PG8_LDB(B0, 1, 0); PG8_LDB(B1, 1, 1); PG8_SCHED; PG8_LDA(At, 1, 0); PG8_STAGE(PG8_SA(0, 1), a2 + hstepA, voffA);
;             PG8_WAIT_V(8); PG8_WAIT_L(0); PG8_BAR; PG8_MMA(0, 0, At, B0); PG8_MMA(0, 1, At, B1); PG8_BAR; PG8_SCHED;
	s_add_i32 s45, 0, 0x18000
	v_add_u32_e32 v155, s45, v143
	s_add_i32 s46, 0, 0x1c000
	ds_read_b128 v[146:149], v155
	ds_read_b128 v[156:159], v155 offset:1024
	ds_read_b128 v[160:163], v155 offset:2048
	ds_read_b128 v[164:167], v155 offset:3072
	v_add_u32_e32 v155, s46, v143
	ds_read_b128 v[168:171], v155
	ds_read_b128 v[172:175], v155 offset:1024
	ds_read_b128 v[176:179], v155 offset:2048
	ds_read_b128 v[180:183], v155 offset:3072
	s_add_u32 s22, s22, 0x40000
	s_addc_u32 s23, s23, 0
	s_mov_b32 m0, s34
	v_lshl_add_u64 v[210:211], s[22:23], 0, v[134:135]
	ds_read_b128 v[184:187], v145 offset:32768
	ds_read_b128 v[188:191], v145 offset:33792
	ds_read_b128 v[192:195], v145 offset:34816
	ds_read_b128 v[196:199], v145 offset:35840
	ds_read_b128 v[218:221], v145 offset:36864
	ds_read_b128 v[222:225], v145 offset:37888
	ds_read_b128 v[226:229], v145 offset:38912
	ds_read_b128 v[230:233], v145 offset:39936
	global_load_lds_dwordx4 v[210:211], off
	v_lshl_add_u64 v[210:211], s[22:23], 0, v[132:133]
	s_mov_b32 m0, s35
	s_nop 0
	global_load_lds_dwordx4 v[210:211], off
	s_waitcnt vmcnt(8)
	s_waitcnt lgkmcnt(0)
	s_barrier
	s_waitcnt lgkmcnt(0)
	v_mfma_f32_16x16x32_bf16 v[126:129], v[146:149], v[184:187], v[126:129]
	v_mfma_f32_16x16x32_bf16 v[122:125], v[160:163], v[184:187], v[122:125]
	v_mfma_f32_16x16x32_bf16 v[110:113], v[146:149], v[192:195], v[110:113]
	v_mfma_f32_16x16x32_bf16 v[106:109], v[160:163], v[192:195], v[106:109]
	v_mfma_f32_16x16x32_bf16 v[94:97], v[146:149], v[218:221], v[94:97]
	v_mfma_f32_16x16x32_bf16 v[90:93], v[160:163], v[218:221], v[90:93]
	v_mfma_f32_16x16x32_bf16 v[78:81], v[146:149], v[226:229], v[78:81]
	v_mfma_f32_16x16x32_bf16 v[74:77], v[160:163], v[226:229], v[74:77]
	v_mfma_f32_16x16x32_bf16 v[126:129], v[156:159], v[188:191], v[126:129]
	v_mfma_f32_16x16x32_bf16 v[122:125], v[164:167], v[188:191], v[122:125]
	v_mfma_f32_16x16x32_bf16 v[110:113], v[156:159], v[196:199], v[110:113]
	v_mfma_f32_16x16x32_bf16 v[106:109], v[164:167], v[196:199], v[106:109]
	v_mfma_f32_16x16x32_bf16 v[94:97], v[156:159], v[222:225], v[94:97]
	v_mfma_f32_16x16x32_bf16 v[90:93], v[164:167], v[222:225], v[90:93]
	v_mfma_f32_16x16x32_bf16 v[78:81], v[156:159], v[230:233], v[78:81]
	v_mfma_f32_16x16x32_bf16 v[74:77], v[164:167], v[230:233], v[74:77]
	v_mfma_f32_16x16x32_bf16 v[118:121], v[168:171], v[184:187], v[118:121]
	v_mfma_f32_16x16x32_bf16 v[114:117], v[176:179], v[184:187], v[114:117]
	v_mfma_f32_16x16x32_bf16 v[102:105], v[168:171], v[192:195], v[102:105]
	v_mfma_f32_16x16x32_bf16 v[98:101], v[176:179], v[192:195], v[98:101]
	v_mfma_f32_16x16x32_bf16 v[86:89], v[168:171], v[218:221], v[86:89]
	v_mfma_f32_16x16x32_bf16 v[82:85], v[176:179], v[218:221], v[82:85]
	v_mfma_f32_16x16x32_bf16 v[70:73], v[168:171], v[226:229], v[70:73]
	v_mfma_f32_16x16x32_bf16 v[66:69], v[176:179], v[226:229], v[66:69]
	v_mfma_f32_16x16x32_bf16 v[118:121], v[172:175], v[188:191], v[118:121]
	v_mfma_f32_16x16x32_bf16 v[114:117], v[180:183], v[188:191], v[114:117]
	v_mfma_f32_16x16x32_bf16 v[102:105], v[172:175], v[196:199], v[102:105]
	v_mfma_f32_16x16x32_bf16 v[98:101], v[180:183], v[196:199], v[98:101]
	v_mfma_f32_16x16x32_bf16 v[86:89], v[172:175], v[222:225], v[86:89]
	v_mfma_f32_16x16x32_bf16 v[82:85], v[180:183], v[222:225], v[82:85]
	v_mfma_f32_16x16x32_bf16 v[70:73], v[172:175], v[230:233], v[70:73]
	v_mfma_f32_16x16x32_bf16 v[66:69], v[180:183], v[230:233], v[66:69]
	s_barrier
; #define PG8_STAGE(bufoff, gbase, voff) do { _Pragma("unroll") for (int _i = 0; _i < 2; ++_i) \
;         __builtin_amdgcn_global_load_lds((const unsigned*)((const char*)(gbase) + (voff)[_i]), (LAS unsigned*)(lds + (bufoff) + ldsw + _i * 8192), 16, 0, 0); } while (0)
; #define PG8_LDA(dst, b, h) do { _Pragma("unroll") for (int m = 0; m < 4; ++m) _Pragma("unroll") for (int k = 0; k < 2; ++k) dst[m][k] = *(const LAS bf16x8*)(lds + PG8_SA(b, h) + aoff + m * 2048 + k * 1024); } while (0)
; #define PG8_MMA(ai, bj, At, Bt) do { __builtin_amdgcn_s_setprio(1); _Pragma("unroll") for (int m = 0; m < 4; ++m) _Pragma("unroll") for (int n = 0; n < 2; ++n) _Pragma("unroll") for (int k = 0; k < 2; ++k) \
;         acc[ai][bj][m][n] = __builtin_amdgcn_mfma_f32_16x16x32_bf16(Bt[n][k], At[m][k], acc[ai][bj][m][n], 0, 0, 0); __builtin_amdgcn_s_setprio(0); } while (0)
; #define PG8_WAIT_V(n) asm volatile("s_waitcnt vmcnt(" #n ")" ::: "memory")
; #define PG8_WAIT_L(n) asm volatile("s_waitcnt lgkmcnt(" #n ")" ::: "memory")
; #define PG8_BAR __builtin_amdgcn_s_barrier()
; #define PG8_SCHED __builtin_amdgcn_sched_barrier(0)
; template <class Epi>
; DI void gemm_phase(ldsp lds, const Gemm g, const StaticOrder S, const Epi E) {
;     ...
;             PG8_LDA(At, 1, 1); PG8_STAGE(PG8_SB(1, 0), b3, voffB); PG8_STAGE(PG8_SB(1, 1), b3 + hstepB, voffB); PG8_STAGE(PG8_SA(1, 0), a3, voffA);
;             PG8_WAIT_V(8); PG8_WAIT_L(0); PG8_BAR; PG8_MMA(1, 0, At, B0); PG8_MMA(1, 1, At, B1); PG8_BAR; PG8_SCHED;
;         }
;         if (wr == 0) PG8_BAR;
;         E(acc, cur, wr, wc, fr, fq);
;         if (!has_next) break;
	s_add_i32 s22, s45, s31
	v_lshl_add_u64 v[140:141], v[140:141], 0, s[88:89]
	s_mov_b32 m0, s22
	ds_read_b128 v[184:187], v145 offset:49152
	ds_read_b128 v[188:191], v145 offset:50176
	ds_read_b128 v[192:195], v145 offset:51200
	ds_read_b128 v[196:199], v145 offset:52224
	ds_read_b128 v[218:221], v145 offset:53248
	ds_read_b128 v[222:225], v145 offset:54272
	ds_read_b128 v[226:229], v145 offset:55296
	ds_read_b128 v[230:233], v145 offset:56320
	global_load_lds_dwordx4 v[140:141], off
	s_add_i32 m0, s22, 0x2000
	s_add_u32 s20, s20, 0x40080
	v_lshl_add_u64 v[140:141], v[150:151], 0, s[88:89]
	s_addc_u32 s21, s21, 0
	s_add_i32 s22, s46, s31
	global_load_lds_dwordx4 v[140:141], off
	v_lshl_add_u64 v[140:141], s[20:21], 0, v[0:1]
	s_mov_b32 m0, s22
	s_nop 0
	global_load_lds_dwordx4 v[140:141], off
	v_lshl_add_u64 v[140:141], s[20:21], 0, v[130:131]
	s_add_i32 m0, s22, 0x2000
	s_nop 0
	global_load_lds_dwordx4 v[140:141], off
	v_lshl_add_u64 v[140:141], v[206:207], 0, s[88:89]
	s_mov_b32 m0, s36
	s_nop 0
	global_load_lds_dwordx4 v[140:141], off
	v_lshl_add_u64 v[140:141], v[208:209], 0, s[88:89]
	s_mov_b32 m0, s37
	s_nop 0
	global_load_lds_dwordx4 v[140:141], off
	s_waitcnt vmcnt(8)
	s_waitcnt lgkmcnt(0)
	s_barrier
	s_waitcnt lgkmcnt(0)
	v_mfma_f32_16x16x32_bf16 v[62:65], v[146:149], v[184:187], v[62:65]
	v_mfma_f32_16x16x32_bf16 v[58:61], v[160:163], v[184:187], v[58:61]
	v_mfma_f32_16x16x32_bf16 v[46:49], v[146:149], v[192:195], v[46:49]
	v_mfma_f32_16x16x32_bf16 v[42:45], v[160:163], v[192:195], v[42:45]
	v_mfma_f32_16x16x32_bf16 v[30:33], v[146:149], v[218:221], v[30:33]
	v_mfma_f32_16x16x32_bf16 v[26:29], v[160:163], v[218:221], v[26:29]
	v_mfma_f32_16x16x32_bf16 v[14:17], v[146:149], v[226:229], v[14:17]
	v_mfma_f32_16x16x32_bf16 v[10:13], v[160:163], v[226:229], v[10:13]
	v_mfma_f32_16x16x32_bf16 v[62:65], v[156:159], v[188:191], v[62:65]
	v_mfma_f32_16x16x32_bf16 v[58:61], v[164:167], v[188:191], v[58:61]
	v_mfma_f32_16x16x32_bf16 v[46:49], v[156:159], v[196:199], v[46:49]
	v_mfma_f32_16x16x32_bf16 v[42:45], v[164:167], v[196:199], v[42:45]
	v_mfma_f32_16x16x32_bf16 v[30:33], v[156:159], v[222:225], v[30:33]
	v_mfma_f32_16x16x32_bf16 v[26:29], v[164:167], v[222:225], v[26:29]
	v_mfma_f32_16x16x32_bf16 v[14:17], v[156:159], v[230:233], v[14:17]
	v_mfma_f32_16x16x32_bf16 v[10:13], v[164:167], v[230:233], v[10:13]
	v_mfma_f32_16x16x32_bf16 v[54:57], v[168:171], v[184:187], v[54:57]
	v_mfma_f32_16x16x32_bf16 v[50:53], v[176:179], v[184:187], v[50:53]
	v_mfma_f32_16x16x32_bf16 v[38:41], v[168:171], v[192:195], v[38:41]
	v_mfma_f32_16x16x32_bf16 v[34:37], v[176:179], v[192:195], v[34:37]
	v_mfma_f32_16x16x32_bf16 v[22:25], v[168:171], v[218:221], v[22:25]
	v_mfma_f32_16x16x32_bf16 v[18:21], v[176:179], v[218:221], v[18:21]
	v_mfma_f32_16x16x32_bf16 v[6:9], v[168:171], v[226:229], v[6:9]
	v_mfma_f32_16x16x32_bf16 v[2:5], v[176:179], v[226:229], v[2:5]
	v_mfma_f32_16x16x32_bf16 v[54:57], v[172:175], v[188:191], v[54:57]
	v_mfma_f32_16x16x32_bf16 v[50:53], v[180:183], v[188:191], v[50:53]
	v_mfma_f32_16x16x32_bf16 v[38:41], v[172:175], v[196:199], v[38:41]
	v_mfma_f32_16x16x32_bf16 v[34:37], v[180:183], v[196:199], v[34:37]
	v_mfma_f32_16x16x32_bf16 v[22:25], v[172:175], v[222:225], v[22:25]
	v_mfma_f32_16x16x32_bf16 v[18:21], v[180:183], v[222:225], v[18:21]
	v_mfma_f32_16x16x32_bf16 v[6:9], v[172:175], v[230:233], v[6:9]
	v_mfma_f32_16x16x32_bf16 v[2:5], v[180:183], v[230:233], v[2:5]
	s_barrier
	s_add_i32 s44, s44, 2
	s_add_u32 s18, s18, 0x100
	s_addc_u32 s19, s19, 0
	s_add_u32 s42, s42, 0x100
	s_addc_u32 s43, s43, 0
	s_cmp_gt_u32 s44, 13
	s_cbranch_scc0 .LBB0_187
	s_setprio 0
	s_and_b64 vcc, exec, s[6:7]
	s_cbranch_vccz .LBB0_190
	s_barrier

; #define PG8_STAGE(bufoff, gbase, voff) do { _Pragma("unroll") for (int _i = 0; _i < 2; ++_i) \
;         __builtin_amdgcn_global_load_lds((const unsigned*)((const char*)(gbase) + (voff)[_i]), (LAS unsigned*)(lds + (bufoff) + ldsw + _i * 8192), 16, 0, 0); } while (0)
; #define PG8_LDA(dst, b, h) do { _Pragma("unroll") for (int m = 0; m < 4; ++m) _Pragma("unroll") for (int k = 0; k < 2; ++k) dst[m][k] = *(const LAS bf16x8*)(lds + PG8_SA(b, h) + aoff + m * 2048 + k * 1024); } while (0)
; #define PG8_LDB(dst, b, h) do { _Pragma("unroll") for (int n = 0; n < 2; ++n) _Pragma("unroll") for (int k = 0; k < 2; ++k) dst[n][k] = *(const LAS bf16x8*)(lds + PG8_SB(b, h) + boff + n * 2048 + k * 1024); } while (0)
; #define PG8_MMA(ai, bj, At, Bt) do { __builtin_amdgcn_s_setprio(1); _Pragma("unroll") for (int m = 0; m < 4; ++m) _Pragma("unroll") for (int n = 0; n < 2; ++n) _Pragma("unroll") for (int k = 0; k < 2; ++k) \
;         acc[ai][bj][m][n] = __builtin_amdgcn_mfma_f32_16x16x32_bf16(Bt[n][k], At[m][k], acc[ai][bj][m][n], 0, 0, 0); __builtin_amdgcn_s_setprio(0); } while (0)
; #define PG8_WAIT_V(n) asm volatile("s_waitcnt vmcnt(" #n ")" ::: "memory")
; #define PG8_WAIT_L(n) asm volatile("s_waitcnt lgkmcnt(" #n ")" ::: "memory")
; #define PG8_BAR __builtin_amdgcn_s_barrier()
; #define PG8_SCHED __builtin_amdgcn_sched_barrier(0)
; template <class Epi>
; DI void gemm_phase(ldsp lds, const Gemm g, const StaticOrder S, const Epi E) {
;     ...
;         for (int t = 0; t < nt; t += 2) {
;             const bool last = (t == nt - 2);
;             const char* a1 = cA + (size_t)(t + 1) * kstep;
;             const char* a2 = last ? nA : cA + (size_t)(t + 2) * kstep; const char* b2 = last ? nB : cB + (size_t)(t + 2) * kstep;
;             const char* a3 = a2 + kstep; const char* b3 = b2 + kstep;
;             PG8_LDB(B0, 0, 0); PG8_LDB(B1, 0, 1); PG8_SCHED; PG8_LDA(At, 0, 0); PG8_STAGE(PG8_SA(1, 1), a1 + hstepA, voffA);
;             PG8_WAIT_V(8); PG8_WAIT_L(0); PG8_BAR; PG8_MMA(0, 0, At, B0); PG8_MMA(0, 1, At, B1); PG8_BAR; PG8_SCHED;
;     ...
;         for (int a = 0; a < 2; ++a)
; #pragma unroll
;             for (int b = 0; b < 2; ++b)
; #pragma unroll
;                 for (int m = 0; m < 4; ++m)
; #pragma unroll
;                     for (int n = 0; n < 2; ++n) acc[a][b][m][n] = (f32x4){0.f, 0.f, 0.f, 0.f};
.LBB0_414:
	s_add_u32 s4, s28, 0x80
	s_addc_u32 s5, s29, 0
	s_add_u32 s28, s26, 0x100
	v_mov_b32_e32 v2, 0
	s_addc_u32 s29, s27, 0
	s_mov_b32 s26, 0
	v_mov_b32_e32 v3, v2
	v_mov_b32_e32 v4, v2
	v_mov_b32_e32 v5, v2
	v_mov_b32_e32 v6, v2
	v_mov_b32_e32 v7, v2
	v_mov_b32_e32 v8, v2
	v_mov_b32_e32 v9, v2
	v_mov_b32_e32 v14, v2
	v_mov_b32_e32 v15, v2
	v_mov_b32_e32 v16, v2
	v_mov_b32_e32 v17, v2
	v_mov_b32_e32 v22, v2
	v_mov_b32_e32 v23, v2
	v_mov_b32_e32 v24, v2
	v_mov_b32_e32 v25, v2
	v_mov_b32_e32 v30, v2
	v_mov_b32_e32 v31, v2
	v_mov_b32_e32 v32, v2
	v_mov_b32_e32 v33, v2
	v_mov_b32_e32 v38, v2
	v_mov_b32_e32 v39, v2
	v_mov_b32_e32 v40, v2
	v_mov_b32_e32 v41, v2
	v_mov_b32_e32 v46, v2
	v_mov_b32_e32 v47, v2
	v_mov_b32_e32 v48, v2
	v_mov_b32_e32 v49, v2
	v_mov_b32_e32 v54, v2
	v_mov_b32_e32 v55, v2
	v_mov_b32_e32 v56, v2
	v_mov_b32_e32 v57, v2
	v_mov_b32_e32 v10, v2
	v_mov_b32_e32 v11, v2
	v_mov_b32_e32 v12, v2
	v_mov_b32_e32 v13, v2
	v_mov_b32_e32 v18, v2
	v_mov_b32_e32 v19, v2
	v_mov_b32_e32 v20, v2
	v_mov_b32_e32 v21, v2
	v_mov_b32_e32 v26, v2
	v_mov_b32_e32 v27, v2
	v_mov_b32_e32 v28, v2
	v_mov_b32_e32 v29, v2
	v_mov_b32_e32 v34, v2
	v_mov_b32_e32 v35, v2
	v_mov_b32_e32 v36, v2
	v_mov_b32_e32 v37, v2
	v_mov_b32_e32 v42, v2
	v_mov_b32_e32 v43, v2
	v_mov_b32_e32 v44, v2
	v_mov_b32_e32 v45, v2
	v_mov_b32_e32 v50, v2
	v_mov_b32_e32 v51, v2
	v_mov_b32_e32 v52, v2
	v_mov_b32_e32 v53, v2
	v_mov_b32_e32 v58, v2
	v_mov_b32_e32 v59, v2
	v_mov_b32_e32 v60, v2
	v_mov_b32_e32 v61, v2
	v_mov_b32_e32 v62, v2
	v_mov_b32_e32 v63, v2
	v_mov_b32_e32 v64, v2
	v_mov_b32_e32 v65, v2
	v_mov_b32_e32 v66, v2
	v_mov_b32_e32 v67, v2
	v_mov_b32_e32 v68, v2
	v_mov_b32_e32 v69, v2
	v_mov_b32_e32 v70, v2
	v_mov_b32_e32 v71, v2
	v_mov_b32_e32 v72, v2
	v_mov_b32_e32 v73, v2
	v_mov_b32_e32 v78, v2
	v_mov_b32_e32 v79, v2
	v_mov_b32_e32 v80, v2
	v_mov_b32_e32 v81, v2
	v_mov_b32_e32 v86, v2
	v_mov_b32_e32 v87, v2
	v_mov_b32_e32 v88, v2
	v_mov_b32_e32 v89, v2
	v_mov_b32_e32 v94, v2
	v_mov_b32_e32 v95, v2
	v_mov_b32_e32 v96, v2
	v_mov_b32_e32 v97, v2
	v_mov_b32_e32 v102, v2
	v_mov_b32_e32 v103, v2
	v_mov_b32_e32 v104, v2
	v_mov_b32_e32 v105, v2
	v_mov_b32_e32 v110, v2
	v_mov_b32_e32 v111, v2
	v_mov_b32_e32 v112, v2
	v_mov_b32_e32 v113, v2
	v_mov_b32_e32 v118, v2
	v_mov_b32_e32 v119, v2
	v_mov_b32_e32 v120, v2
	v_mov_b32_e32 v121, v2
	v_mov_b32_e32 v74, v2
	v_mov_b32_e32 v75, v2
	v_mov_b32_e32 v76, v2
	v_mov_b32_e32 v77, v2
	v_mov_b32_e32 v82, v2
	v_mov_b32_e32 v83, v2
	v_mov_b32_e32 v84, v2
	v_mov_b32_e32 v85, v2
	v_mov_b32_e32 v90, v2
	v_mov_b32_e32 v91, v2
	v_mov_b32_e32 v92, v2
	v_mov_b32_e32 v93, v2
	v_mov_b32_e32 v98, v2
	v_mov_b32_e32 v99, v2
	v_mov_b32_e32 v100, v2
	v_mov_b32_e32 v101, v2
	v_mov_b32_e32 v106, v2
	v_mov_b32_e32 v107, v2
	v_mov_b32_e32 v108, v2
	v_mov_b32_e32 v109, v2
	v_mov_b32_e32 v114, v2
	v_mov_b32_e32 v115, v2
	v_mov_b32_e32 v116, v2
	v_mov_b32_e32 v117, v2
	v_mov_b32_e32 v122, v2
	v_mov_b32_e32 v123, v2
	v_mov_b32_e32 v124, v2
	v_mov_b32_e32 v125, v2
	v_mov_b32_e32 v126, v2
	v_mov_b32_e32 v127, v2
	v_mov_b32_e32 v128, v2
	v_mov_b32_e32 v129, v2
	v_readfirstlane_b32 s32, v153
	s_nop 3
	s_lshr_b32 s32, s32, 6
	s_cmp_ge_u32 s32, 4
	s_cbranch_scc0 .Lgemm_prio_skip2
	s_setprio 1
.Lgemm_prio_skip2:
.LBB0_415:
	s_add_i32 s59, s26, 2
	s_add_u32 s60, s4, 0x80
	s_addc_u32 s27, s5, 0
	s_add_i32 s62, 0, 0x10000
	s_cmp_eq_u32 s50, s26
	s_cselect_b32 s27, s23, s27
	s_cselect_b32 s26, s22, s60
	v_add_u32_e32 v140, s62, v143
	s_cselect_b32 s61, s25, s29
	s_cselect_b32 s60, s24, s28
	s_add_i32 s63, 0, 0x14000
	ds_read_b128 v[146:149], v140
	ds_read_b128 v[156:159], v140 offset:1024
	ds_read_b128 v[160:163], v140 offset:2048
	ds_read_b128 v[164:167], v140 offset:3072
	v_add_u32_e32 v140, s63, v143
	ds_read_b128 v[168:171], v140
	ds_read_b128 v[172:175], v140 offset:1024
	ds_read_b128 v[176:179], v140 offset:2048
	ds_read_b128 v[180:183], v140 offset:3072
	v_lshl_add_u64 v[140:141], s[4:5], 0, v[136:137]
	s_add_i32 m0, s43, 0xc000
	ds_read_b128 v[184:187], v145
	ds_read_b128 v[188:191], v145 offset:1024
	ds_read_b128 v[192:195], v145 offset:2048
	ds_read_b128 v[196:199], v145 offset:3072
	ds_read_b128 v[218:221], v145 offset:4096
	ds_read_b128 v[222:225], v145 offset:5120
	ds_read_b128 v[226:229], v145 offset:6144
	ds_read_b128 v[230:233], v145 offset:7168
	global_load_lds_dwordx4 v[140:141], off
	v_lshl_add_u64 v[140:141], s[4:5], 0, v[138:139]
	s_add_i32 m0, s43, 0xe000
	s_nop 0
	global_load_lds_dwordx4 v[140:141], off
	s_waitcnt vmcnt(8)
	s_waitcnt lgkmcnt(0)
	s_barrier
; #define PG8_STAGE(bufoff, gbase, voff) do { _Pragma("unroll") for (int _i = 0; _i < 2; ++_i) \
;         __builtin_amdgcn_global_load_lds((const unsigned*)((const char*)(gbase) + (voff)[_i]), (LAS unsigned*)(lds + (bufoff) + ldsw + _i * 8192), 16, 0, 0); } while (0)
; #define PG8_LDA(dst, b, h) do { _Pragma("unroll") for (int m = 0; m < 4; ++m) _Pragma("unroll") for (int k = 0; k < 2; ++k) dst[m][k] = *(const LAS bf16x8*)(lds + PG8_SA(b, h) + aoff + m * 2048 + k * 1024); } while (0)
; #define PG8_MMA(ai, bj, At, Bt) do { __builtin_amdgcn_s_setprio(1); _Pragma("unroll") for (int m = 0; m < 4; ++m) _Pragma("unroll") for (int n = 0; n < 2; ++n) _Pragma("unroll") for (int k = 0; k < 2; ++k) \
;         acc[ai][bj][m][n] = __builtin_amdgcn_mfma_f32_16x16x32_bf16(Bt[n][k], At[m][k], acc[ai][bj][m][n], 0, 0, 0); __builtin_amdgcn_s_setprio(0); } while (0)
; #define PG8_WAIT_V(n) asm volatile("s_waitcnt vmcnt(" #n ")" ::: "memory")
; #define PG8_WAIT_L(n) asm volatile("s_waitcnt lgkmcnt(" #n ")" ::: "memory")
; #define PG8_BAR __builtin_amdgcn_s_barrier()
; #define PG8_SCHED __builtin_amdgcn_sched_barrier(0)
; template <class Epi>
; DI void gemm_phase(ldsp lds, const Gemm g, const StaticOrder S, const Epi E) {
;     ...
;             PG8_WAIT_V(8); PG8_WAIT_L(0); PG8_BAR; PG8_MMA(0, 0, At, B0); PG8_MMA(0, 1, At, B1); PG8_BAR; PG8_SCHED;
;             PG8_LDA(At, 0, 1); PG8_STAGE(PG8_SB(0, 0), b2, voffB); PG8_STAGE(PG8_SB(0, 1), b2 + hstepB, voffB); PG8_STAGE(PG8_SA(0, 0), a2, voffA);
;             PG8_WAIT_V(8); PG8_WAIT_L(0); PG8_BAR; PG8_MMA(1, 0, At, B0); PG8_MMA(1, 1, At, B1); PG8_BAR; PG8_SCHED;
	s_waitcnt lgkmcnt(0)
	v_mfma_f32_16x16x32_bf16 v[126:129], v[146:149], v[184:187], v[126:129]
	v_mfma_f32_16x16x32_bf16 v[122:125], v[160:163], v[184:187], v[122:125]
	v_mfma_f32_16x16x32_bf16 v[114:117], v[146:149], v[192:195], v[114:117]
	v_mfma_f32_16x16x32_bf16 v[106:109], v[160:163], v[192:195], v[106:109]
	v_mfma_f32_16x16x32_bf16 v[98:101], v[146:149], v[218:221], v[98:101]
	v_mfma_f32_16x16x32_bf16 v[90:93], v[160:163], v[218:221], v[90:93]
	v_mfma_f32_16x16x32_bf16 v[82:85], v[146:149], v[226:229], v[82:85]
	v_mfma_f32_16x16x32_bf16 v[74:77], v[160:163], v[226:229], v[74:77]
	v_mfma_f32_16x16x32_bf16 v[126:129], v[156:159], v[188:191], v[126:129]
	v_mfma_f32_16x16x32_bf16 v[122:125], v[164:167], v[188:191], v[122:125]
	v_mfma_f32_16x16x32_bf16 v[114:117], v[156:159], v[196:199], v[114:117]
	v_mfma_f32_16x16x32_bf16 v[106:109], v[164:167], v[196:199], v[106:109]
	v_mfma_f32_16x16x32_bf16 v[98:101], v[156:159], v[222:225], v[98:101]
	v_mfma_f32_16x16x32_bf16 v[90:93], v[164:167], v[222:225], v[90:93]
	v_mfma_f32_16x16x32_bf16 v[82:85], v[156:159], v[230:233], v[82:85]
	v_mfma_f32_16x16x32_bf16 v[74:77], v[164:167], v[230:233], v[74:77]
	v_mfma_f32_16x16x32_bf16 v[118:121], v[168:171], v[184:187], v[118:121]
	v_mfma_f32_16x16x32_bf16 v[110:113], v[176:179], v[184:187], v[110:113]
	v_mfma_f32_16x16x32_bf16 v[102:105], v[168:171], v[192:195], v[102:105]
	v_mfma_f32_16x16x32_bf16 v[94:97], v[176:179], v[192:195], v[94:97]
	v_mfma_f32_16x16x32_bf16 v[86:89], v[168:171], v[218:221], v[86:89]
	v_mfma_f32_16x16x32_bf16 v[78:81], v[176:179], v[218:221], v[78:81]
	v_mfma_f32_16x16x32_bf16 v[70:73], v[168:171], v[226:229], v[70:73]
	v_mfma_f32_16x16x32_bf16 v[66:69], v[176:179], v[226:229], v[66:69]
	v_mfma_f32_16x16x32_bf16 v[118:121], v[172:175], v[188:191], v[118:121]
	v_mfma_f32_16x16x32_bf16 v[110:113], v[180:183], v[188:191], v[110:113]
	v_mfma_f32_16x16x32_bf16 v[102:105], v[172:175], v[196:199], v[102:105]
	v_mfma_f32_16x16x32_bf16 v[94:97], v[180:183], v[196:199], v[94:97]
	v_mfma_f32_16x16x32_bf16 v[86:89], v[172:175], v[222:225], v[86:89]
	v_mfma_f32_16x16x32_bf16 v[78:81], v[180:183], v[222:225], v[78:81]
	v_mfma_f32_16x16x32_bf16 v[70:73], v[172:175], v[230:233], v[70:73]
	v_mfma_f32_16x16x32_bf16 v[66:69], v[180:183], v[230:233], v[66:69]
	s_barrier
	s_add_i32 s62, s62, s42
	v_lshl_add_u64 v[140:141], s[60:61], 0, v[0:1]
	s_mov_b32 m0, s62
	ds_read_b128 v[184:187], v145 offset:16384
	ds_read_b128 v[188:191], v145 offset:17408
	ds_read_b128 v[192:195], v145 offset:18432
	ds_read_b128 v[196:199], v145 offset:19456
	ds_read_b128 v[218:221], v145 offset:20480
	ds_read_b128 v[222:225], v145 offset:21504
	ds_read_b128 v[226:229], v145 offset:22528
	ds_read_b128 v[230:233], v145 offset:23552
	global_load_lds_dwordx4 v[140:141], off
	s_add_i32 m0, s62, 0x2000
	v_lshl_add_u64 v[150:151], s[60:61], 0, v[134:135]
	s_add_u32 s60, s60, s39
	s_addc_u32 s61, s61, 0
	s_add_i32 s62, s63, s42
	global_load_lds_dwordx4 v[150:151], off
	v_lshl_add_u64 v[206:207], s[60:61], 0, v[0:1]
	s_mov_b32 m0, s62
	v_lshl_add_u64 v[208:209], s[60:61], 0, v[134:135]
	global_load_lds_dwordx4 v[206:207], off
	s_add_i32 m0, s62, 0x2000
	v_lshl_add_u64 v[210:211], s[26:27], 0, v[130:131]
	global_load_lds_dwordx4 v[208:209], off
	s_mov_b32 m0, s43
	v_lshl_add_u64 v[212:213], s[26:27], 0, v[132:133]
	global_load_lds_dwordx4 v[210:211], off
	s_mov_b32 m0, s44
	s_nop 0
	global_load_lds_dwordx4 v[212:213], off
	s_waitcnt vmcnt(8)
	s_waitcnt lgkmcnt(0)
	s_barrier
	s_waitcnt lgkmcnt(0)
	v_mfma_f32_16x16x32_bf16 v[62:65], v[146:149], v[184:187], v[62:65]
	v_mfma_f32_16x16x32_bf16 v[58:61], v[160:163], v[184:187], v[58:61]
	v_mfma_f32_16x16x32_bf16 v[50:53], v[146:149], v[192:195], v[50:53]
	v_mfma_f32_16x16x32_bf16 v[42:45], v[160:163], v[192:195], v[42:45]
	v_mfma_f32_16x16x32_bf16 v[34:37], v[146:149], v[218:221], v[34:37]
	v_mfma_f32_16x16x32_bf16 v[26:29], v[160:163], v[218:221], v[26:29]
	v_mfma_f32_16x16x32_bf16 v[18:21], v[146:149], v[226:229], v[18:21]
	v_mfma_f32_16x16x32_bf16 v[10:13], v[160:163], v[226:229], v[10:13]
	v_mfma_f32_16x16x32_bf16 v[62:65], v[156:159], v[188:191], v[62:65]
	v_mfma_f32_16x16x32_bf16 v[58:61], v[164:167], v[188:191], v[58:61]
	v_mfma_f32_16x16x32_bf16 v[50:53], v[156:159], v[196:199], v[50:53]
	v_mfma_f32_16x16x32_bf16 v[42:45], v[164:167], v[196:199], v[42:45]
	v_mfma_f32_16x16x32_bf16 v[34:37], v[156:159], v[222:225], v[34:37]
	v_mfma_f32_16x16x32_bf16 v[26:29], v[164:167], v[222:225], v[26:29]
	v_mfma_f32_16x16x32_bf16 v[18:21], v[156:159], v[230:233], v[18:21]
	v_mfma_f32_16x16x32_bf16 v[10:13], v[164:167], v[230:233], v[10:13]
	v_mfma_f32_16x16x32_bf16 v[54:57], v[168:171], v[184:187], v[54:57]
	v_mfma_f32_16x16x32_bf16 v[46:49], v[176:179], v[184:187], v[46:49]
	v_mfma_f32_16x16x32_bf16 v[38:41], v[168:171], v[192:195], v[38:41]
	v_mfma_f32_16x16x32_bf16 v[30:33], v[176:179], v[192:195], v[30:33]
	v_mfma_f32_16x16x32_bf16 v[22:25], v[168:171], v[218:221], v[22:25]
	v_mfma_f32_16x16x32_bf16 v[14:17], v[176:179], v[218:221], v[14:17]
	v_mfma_f32_16x16x32_bf16 v[6:9], v[168:171], v[226:229], v[6:9]
	v_mfma_f32_16x16x32_bf16 v[2:5], v[176:179], v[226:229], v[2:5]
	v_mfma_f32_16x16x32_bf16 v[54:57], v[172:175], v[188:191], v[54:57]
	v_mfma_f32_16x16x32_bf16 v[46:49], v[180:183], v[188:191], v[46:49]
	v_mfma_f32_16x16x32_bf16 v[38:41], v[172:175], v[196:199], v[38:41]
	v_mfma_f32_16x16x32_bf16 v[30:33], v[180:183], v[196:199], v[30:33]
	v_mfma_f32_16x16x32_bf16 v[22:25], v[172:175], v[222:225], v[22:25]
	v_mfma_f32_16x16x32_bf16 v[14:17], v[180:183], v[222:225], v[14:17]
	v_mfma_f32_16x16x32_bf16 v[6:9], v[172:175], v[230:233], v[6:9]
	v_mfma_f32_16x16x32_bf16 v[2:5], v[180:183], v[230:233], v[2:5]
	s_barrier
; #define PG8_STAGE(bufoff, gbase, voff) do { _Pragma("unroll") for (int _i = 0; _i < 2; ++_i) \
;         __builtin_amdgcn_global_load_lds((const unsigned*)((const char*)(gbase) + (voff)[_i]), (LAS unsigned*)(lds + (bufoff) + ldsw + _i * 8192), 16, 0, 0); } while (0)
; #define PG8_LDA(dst, b, h) do { _Pragma("unroll") for (int m = 0; m < 4; ++m) _Pragma("unroll") for (int k = 0; k < 2; ++k) dst[m][k] = *(const LAS bf16x8*)(lds + PG8_SA(b, h) + aoff + m * 2048 + k * 1024); } while (0)
; #define PG8_LDB(dst, b, h) do { _Pragma("unroll") for (int n = 0; n < 2; ++n) _Pragma("unroll") for (int k = 0; k < 2; ++k) dst[n][k] = *(const LAS bf16x8*)(lds + PG8_SB(b, h) + boff + n * 2048 + k * 1024); } while (0)
; #define PG8_MMA(ai, bj, At, Bt) do { __builtin_amdgcn_s_setprio(1); _Pragma("unroll") for (int m = 0; m < 4; ++m) _Pragma("unroll") for (int n = 0; n < 2; ++n) _Pragma("unroll") for (int k = 0; k < 2; ++k) \
;         acc[ai][bj][m][n] = __builtin_amdgcn_mfma_f32_16x16x32_bf16(Bt[n][k], At[m][k], acc[ai][bj][m][n], 0, 0, 0); __builtin_amdgcn_s_setprio(0); } while (0)
; #define PG8_WAIT_V(n) asm volatile("s_waitcnt vmcnt(" #n ")" ::: "memory")
; #define PG8_WAIT_L(n) asm volatile("s_waitcnt lgkmcnt(" #n ")" ::: "memory")
; #define PG8_BAR __builtin_amdgcn_s_barrier()
; #define PG8_SCHED __builtin_amdgcn_sched_barrier(0)
; template <class Epi>
; DI void gemm_phase(ldsp lds, const Gemm g, const StaticOrder S, const Epi E) {
;     ...
;             PG8_LDB(B0, 1, 0); PG8_LDB(B1, 1, 1); PG8_SCHED; PG8_LDA(At, 1, 0); PG8_STAGE(PG8_SA(0, 1), a2 + hstepA, voffA);
;             PG8_WAIT_V(8); PG8_WAIT_L(0); PG8_BAR; PG8_MMA(0, 0, At, B0); PG8_MMA(0, 1, At, B1); PG8_BAR; PG8_SCHED;
	s_add_i32 s60, 0, 0x18000
	v_add_u32_e32 v155, s60, v143
	s_add_i32 s61, 0, 0x1c000
	ds_read_b128 v[146:149], v155
	ds_read_b128 v[156:159], v155 offset:1024
	ds_read_b128 v[160:163], v155 offset:2048
	ds_read_b128 v[164:167], v155 offset:3072
	v_add_u32_e32 v155, s61, v143
	ds_read_b128 v[168:171], v155
	ds_read_b128 v[172:175], v155 offset:1024
	ds_read_b128 v[176:179], v155 offset:2048
	ds_read_b128 v[180:183], v155 offset:3072
	s_add_u32 s26, s26, s96
	s_addc_u32 s27, s27, 0
	s_mov_b32 m0, s45
	v_lshl_add_u64 v[234:235], s[26:27], 0, v[130:131]
	ds_read_b128 v[184:187], v145 offset:32768
	ds_read_b128 v[188:191], v145 offset:33792
	ds_read_b128 v[192:195], v145 offset:34816
	ds_read_b128 v[196:199], v145 offset:35840
	ds_read_b128 v[218:221], v145 offset:36864
	ds_read_b128 v[222:225], v145 offset:37888
	ds_read_b128 v[226:229], v145 offset:38912
	ds_read_b128 v[230:233], v145 offset:39936
	global_load_lds_dwordx4 v[234:235], off
	v_lshl_add_u64 v[234:235], s[26:27], 0, v[132:133]
	s_mov_b32 m0, s46
	s_nop 0
	global_load_lds_dwordx4 v[234:235], off
	s_waitcnt vmcnt(8)
	s_waitcnt lgkmcnt(0)
	s_barrier
	s_waitcnt lgkmcnt(0)
	v_mfma_f32_16x16x32_bf16 v[126:129], v[146:149], v[184:187], v[126:129]
	v_mfma_f32_16x16x32_bf16 v[122:125], v[160:163], v[184:187], v[122:125]
	v_mfma_f32_16x16x32_bf16 v[114:117], v[146:149], v[192:195], v[114:117]
	v_mfma_f32_16x16x32_bf16 v[106:109], v[160:163], v[192:195], v[106:109]
	v_mfma_f32_16x16x32_bf16 v[98:101], v[146:149], v[218:221], v[98:101]
	v_mfma_f32_16x16x32_bf16 v[90:93], v[160:163], v[218:221], v[90:93]
	v_mfma_f32_16x16x32_bf16 v[82:85], v[146:149], v[226:229], v[82:85]
	v_mfma_f32_16x16x32_bf16 v[74:77], v[160:163], v[226:229], v[74:77]
	v_mfma_f32_16x16x32_bf16 v[126:129], v[156:159], v[188:191], v[126:129]
	v_mfma_f32_16x16x32_bf16 v[122:125], v[164:167], v[188:191], v[122:125]
	v_mfma_f32_16x16x32_bf16 v[114:117], v[156:159], v[196:199], v[114:117]
	v_mfma_f32_16x16x32_bf16 v[106:109], v[164:167], v[196:199], v[106:109]
	v_mfma_f32_16x16x32_bf16 v[98:101], v[156:159], v[222:225], v[98:101]
	v_mfma_f32_16x16x32_bf16 v[90:93], v[164:167], v[222:225], v[90:93]
	v_mfma_f32_16x16x32_bf16 v[82:85], v[156:159], v[230:233], v[82:85]
	v_mfma_f32_16x16x32_bf16 v[74:77], v[164:167], v[230:233], v[74:77]
	v_mfma_f32_16x16x32_bf16 v[118:121], v[168:171], v[184:187], v[118:121]
	v_mfma_f32_16x16x32_bf16 v[110:113], v[176:179], v[184:187], v[110:113]
	v_mfma_f32_16x16x32_bf16 v[102:105], v[168:171], v[192:195], v[102:105]
	v_mfma_f32_16x16x32_bf16 v[94:97], v[176:179], v[192:195], v[94:97]
	v_mfma_f32_16x16x32_bf16 v[86:89], v[168:171], v[218:221], v[86:89]
	v_mfma_f32_16x16x32_bf16 v[78:81], v[176:179], v[218:221], v[78:81]
	v_mfma_f32_16x16x32_bf16 v[70:73], v[168:171], v[226:229], v[70:73]
	v_mfma_f32_16x16x32_bf16 v[66:69], v[176:179], v[226:229], v[66:69]
	v_mfma_f32_16x16x32_bf16 v[118:121], v[172:175], v[188:191], v[118:121]
	v_mfma_f32_16x16x32_bf16 v[110:113], v[180:183], v[188:191], v[110:113]
	v_mfma_f32_16x16x32_bf16 v[102:105], v[172:175], v[196:199], v[102:105]
	v_mfma_f32_16x16x32_bf16 v[94:97], v[180:183], v[196:199], v[94:97]
	v_mfma_f32_16x16x32_bf16 v[86:89], v[172:175], v[222:225], v[86:89]
	v_mfma_f32_16x16x32_bf16 v[78:81], v[180:183], v[222:225], v[78:81]
	v_mfma_f32_16x16x32_bf16 v[70:73], v[172:175], v[230:233], v[70:73]
	v_mfma_f32_16x16x32_bf16 v[66:69], v[180:183], v[230:233], v[66:69]
	s_barrier
; #define PG8_STAGE(bufoff, gbase, voff) do { _Pragma("unroll") for (int _i = 0; _i < 2; ++_i) \
;         __builtin_amdgcn_global_load_lds((const unsigned*)((const char*)(gbase) + (voff)[_i]), (LAS unsigned*)(lds + (bufoff) + ldsw + _i * 8192), 16, 0, 0); } while (0)
; #define PG8_LDA(dst, b, h) do { _Pragma("unroll") for (int m = 0; m < 4; ++m) _Pragma("unroll") for (int k = 0; k < 2; ++k) dst[m][k] = *(const LAS bf16x8*)(lds + PG8_SA(b, h) + aoff + m * 2048 + k * 1024); } while (0)
; #define PG8_MMA(ai, bj, At, Bt) do { __builtin_amdgcn_s_setprio(1); _Pragma("unroll") for (int m = 0; m < 4; ++m) _Pragma("unroll") for (int n = 0; n < 2; ++n) _Pragma("unroll") for (int k = 0; k < 2; ++k) \
;         acc[ai][bj][m][n] = __builtin_amdgcn_mfma_f32_16x16x32_bf16(Bt[n][k], At[m][k], acc[ai][bj][m][n], 0, 0, 0); __builtin_amdgcn_s_setprio(0); } while (0)
; #define PG8_WAIT_V(n) asm volatile("s_waitcnt vmcnt(" #n ")" ::: "memory")
; #define PG8_WAIT_L(n) asm volatile("s_waitcnt lgkmcnt(" #n ")" ::: "memory")
; #define PG8_BAR __builtin_amdgcn_s_barrier()
; #define PG8_SCHED __builtin_amdgcn_sched_barrier(0)
; template <class Epi>
; DI void gemm_phase(ldsp lds, const Gemm g, const StaticOrder S, const Epi E) {
;     ...
;             PG8_LDA(At, 1, 1); PG8_STAGE(PG8_SB(1, 0), b3, voffB); PG8_STAGE(PG8_SB(1, 1), b3 + hstepB, voffB); PG8_STAGE(PG8_SA(1, 0), a3, voffA);
;             PG8_WAIT_V(8); PG8_WAIT_L(0); PG8_BAR; PG8_MMA(1, 0, At, B0); PG8_MMA(1, 1, At, B1); PG8_BAR; PG8_SCHED;
;         }
;         if (wr == 0) PG8_BAR;
;         E(acc, cur, wr, wc, fr, fq);
;         if (!has_next) break;
	s_add_i32 s26, s60, s42
	v_lshl_add_u64 v[140:141], v[140:141], 0, s[88:89]
	s_mov_b32 m0, s26
	ds_read_b128 v[184:187], v145 offset:49152
	ds_read_b128 v[188:191], v145 offset:50176
	ds_read_b128 v[192:195], v145 offset:51200
	ds_read_b128 v[196:199], v145 offset:52224
	ds_read_b128 v[218:221], v145 offset:53248
	ds_read_b128 v[222:225], v145 offset:54272
	ds_read_b128 v[226:229], v145 offset:55296
	ds_read_b128 v[230:233], v145 offset:56320
	global_load_lds_dwordx4 v[140:141], off
	v_lshl_add_u64 v[140:141], v[150:151], 0, s[88:89]
	s_add_i32 m0, s26, 0x2000
	s_add_i32 s26, s61, s42
	global_load_lds_dwordx4 v[140:141], off
	v_lshl_add_u64 v[140:141], v[206:207], 0, s[88:89]
	s_mov_b32 m0, s26
	s_nop 0
	global_load_lds_dwordx4 v[140:141], off
	v_lshl_add_u64 v[140:141], v[208:209], 0, s[88:89]
	s_add_i32 m0, s26, 0x2000
	s_nop 0
	global_load_lds_dwordx4 v[140:141], off
	v_lshl_add_u64 v[140:141], v[210:211], 0, s[88:89]
	s_mov_b32 m0, s47
	s_nop 0
	global_load_lds_dwordx4 v[140:141], off
	v_lshl_add_u64 v[140:141], v[212:213], 0, s[88:89]
	s_mov_b32 m0, s48
	s_nop 0
	global_load_lds_dwordx4 v[140:141], off
	s_waitcnt vmcnt(8)
	s_waitcnt lgkmcnt(0)
	s_barrier
	s_waitcnt lgkmcnt(0)
	v_mfma_f32_16x16x32_bf16 v[62:65], v[146:149], v[184:187], v[62:65]
	v_mfma_f32_16x16x32_bf16 v[58:61], v[160:163], v[184:187], v[58:61]
	v_mfma_f32_16x16x32_bf16 v[50:53], v[146:149], v[192:195], v[50:53]
	v_mfma_f32_16x16x32_bf16 v[42:45], v[160:163], v[192:195], v[42:45]
	v_mfma_f32_16x16x32_bf16 v[34:37], v[146:149], v[218:221], v[34:37]
	v_mfma_f32_16x16x32_bf16 v[26:29], v[160:163], v[218:221], v[26:29]
	v_mfma_f32_16x16x32_bf16 v[18:21], v[146:149], v[226:229], v[18:21]
	v_mfma_f32_16x16x32_bf16 v[10:13], v[160:163], v[226:229], v[10:13]
	v_mfma_f32_16x16x32_bf16 v[62:65], v[156:159], v[188:191], v[62:65]
	v_mfma_f32_16x16x32_bf16 v[58:61], v[164:167], v[188:191], v[58:61]
	v_mfma_f32_16x16x32_bf16 v[50:53], v[156:159], v[196:199], v[50:53]
	v_mfma_f32_16x16x32_bf16 v[42:45], v[164:167], v[196:199], v[42:45]
	v_mfma_f32_16x16x32_bf16 v[34:37], v[156:159], v[222:225], v[34:37]
	v_mfma_f32_16x16x32_bf16 v[26:29], v[164:167], v[222:225], v[26:29]
	v_mfma_f32_16x16x32_bf16 v[18:21], v[156:159], v[230:233], v[18:21]
	v_mfma_f32_16x16x32_bf16 v[10:13], v[164:167], v[230:233], v[10:13]
	v_mfma_f32_16x16x32_bf16 v[54:57], v[168:171], v[184:187], v[54:57]
	v_mfma_f32_16x16x32_bf16 v[46:49], v[176:179], v[184:187], v[46:49]
	v_mfma_f32_16x16x32_bf16 v[38:41], v[168:171], v[192:195], v[38:41]
	v_mfma_f32_16x16x32_bf16 v[30:33], v[176:179], v[192:195], v[30:33]
	v_mfma_f32_16x16x32_bf16 v[22:25], v[168:171], v[218:221], v[22:25]
	v_mfma_f32_16x16x32_bf16 v[14:17], v[176:179], v[218:221], v[14:17]
	v_mfma_f32_16x16x32_bf16 v[6:9], v[168:171], v[226:229], v[6:9]
	v_mfma_f32_16x16x32_bf16 v[2:5], v[176:179], v[226:229], v[2:5]
	v_mfma_f32_16x16x32_bf16 v[54:57], v[172:175], v[188:191], v[54:57]
	v_mfma_f32_16x16x32_bf16 v[46:49], v[180:183], v[188:191], v[46:49]
	v_mfma_f32_16x16x32_bf16 v[38:41], v[172:175], v[196:199], v[38:41]
	v_mfma_f32_16x16x32_bf16 v[30:33], v[180:183], v[196:199], v[30:33]
	v_mfma_f32_16x16x32_bf16 v[22:25], v[172:175], v[222:225], v[22:25]
	v_mfma_f32_16x16x32_bf16 v[14:17], v[180:183], v[222:225], v[14:17]
	v_mfma_f32_16x16x32_bf16 v[6:9], v[172:175], v[230:233], v[6:9]
	v_mfma_f32_16x16x32_bf16 v[2:5], v[180:183], v[230:233], v[2:5]
	s_barrier
	s_add_u32 s4, s4, 0x100
	s_addc_u32 s5, s5, 0
	s_add_u32 s28, s28, 0x100
	s_addc_u32 s29, s29, 0
	s_cmp_ge_u32 s59, s49
	s_mov_b32 s26, s59
	s_cbranch_scc0 .LBB0_415
	s_setprio 0
	s_and_b64 vcc, exec, s[20:21]
	s_cbranch_vccz .LBB0_418
	s_barrier

; #define PG8_STAGE(bufoff, gbase, voff) do { _Pragma("unroll") for (int _i = 0; _i < 2; ++_i) \
;         __builtin_amdgcn_global_load_lds((const unsigned*)((const char*)(gbase) + (voff)[_i]), (LAS unsigned*)(lds + (bufoff) + ldsw + _i * 8192), 16, 0, 0); } while (0)
; #define PG8_LDA(dst, b, h) do { _Pragma("unroll") for (int m = 0; m < 4; ++m) _Pragma("unroll") for (int k = 0; k < 2; ++k) dst[m][k] = *(const LAS bf16x8*)(lds + PG8_SA(b, h) + aoff + m * 2048 + k * 1024); } while (0)
; #define PG8_LDB(dst, b, h) do { _Pragma("unroll") for (int n = 0; n < 2; ++n) _Pragma("unroll") for (int k = 0; k < 2; ++k) dst[n][k] = *(const LAS bf16x8*)(lds + PG8_SB(b, h) + boff + n * 2048 + k * 1024); } while (0)
; #define PG8_MMA(ai, bj, At, Bt) do { __builtin_amdgcn_s_setprio(1); _Pragma("unroll") for (int m = 0; m < 4; ++m) _Pragma("unroll") for (int n = 0; n < 2; ++n) _Pragma("unroll") for (int k = 0; k < 2; ++k) \
;         acc[ai][bj][m][n] = __builtin_amdgcn_mfma_f32_16x16x32_bf16(Bt[n][k], At[m][k], acc[ai][bj][m][n], 0, 0, 0); __builtin_amdgcn_s_setprio(0); } while (0)
; #define PG8_WAIT_V(n) asm volatile("s_waitcnt vmcnt(" #n ")" ::: "memory")
; #define PG8_WAIT_L(n) asm volatile("s_waitcnt lgkmcnt(" #n ")" ::: "memory")
; #define PG8_BAR __builtin_amdgcn_s_barrier()
; #define PG8_SCHED __builtin_amdgcn_sched_barrier(0)
; template <class Epi>
; DI void gemm_phase(ldsp lds, const Gemm g, const StaticOrder S, const Epi E) {
;     ...
;         for (int t = 0; t < nt; t += 2) {
;             const bool last = (t == nt - 2);
;             const char* a1 = cA + (size_t)(t + 1) * kstep;
;             const char* a2 = last ? nA : cA + (size_t)(t + 2) * kstep; const char* b2 = last ? nB : cB + (size_t)(t + 2) * kstep;
;             const char* a3 = a2 + kstep; const char* b3 = b2 + kstep;
;             PG8_LDB(B0, 0, 0); PG8_LDB(B1, 0, 1); PG8_SCHED; PG8_LDA(At, 0, 0); PG8_STAGE(PG8_SA(1, 1), a1 + hstepA, voffA);
;             PG8_WAIT_V(8); PG8_WAIT_L(0); PG8_BAR; PG8_MMA(0, 0, At, B0); PG8_MMA(0, 1, At, B1); PG8_BAR; PG8_SCHED;
;     ...
;         for (int a = 0; a < 2; ++a)
; #pragma unroll
;             for (int b = 0; b < 2; ++b)
; #pragma unroll
;                 for (int m = 0; m < 4; ++m)
; #pragma unroll
;                     for (int n = 0; n < 2; ++n) acc[a][b][m][n] = (f32x4){0.f, 0.f, 0.f, 0.f};
.LBB0_944:
	s_add_u32 s20, s20, 0x80
	s_addc_u32 s21, s21, 0
	s_add_u32 s44, s22, 0x100
	v_mov_b32_e32 v2, 0
	s_addc_u32 s45, s23, 0
	s_mov_b32 s22, 0
	v_mov_b32_e32 v3, v2
	v_mov_b32_e32 v4, v2
	v_mov_b32_e32 v5, v2
	v_mov_b32_e32 v6, v2
	v_mov_b32_e32 v7, v2
	v_mov_b32_e32 v8, v2
	v_mov_b32_e32 v9, v2
	v_mov_b32_e32 v10, v2
	v_mov_b32_e32 v11, v2
	v_mov_b32_e32 v12, v2
	v_mov_b32_e32 v13, v2
	v_mov_b32_e32 v22, v2
	v_mov_b32_e32 v23, v2
	v_mov_b32_e32 v24, v2
	v_mov_b32_e32 v25, v2
	v_mov_b32_e32 v26, v2
	v_mov_b32_e32 v27, v2
	v_mov_b32_e32 v28, v2
	v_mov_b32_e32 v29, v2
	v_mov_b32_e32 v38, v2
	v_mov_b32_e32 v39, v2
	v_mov_b32_e32 v40, v2
	v_mov_b32_e32 v41, v2
	v_mov_b32_e32 v42, v2
	v_mov_b32_e32 v43, v2
	v_mov_b32_e32 v44, v2
	v_mov_b32_e32 v45, v2
	v_mov_b32_e32 v54, v2
	v_mov_b32_e32 v55, v2
	v_mov_b32_e32 v56, v2
	v_mov_b32_e32 v57, v2
	v_mov_b32_e32 v14, v2
	v_mov_b32_e32 v15, v2
	v_mov_b32_e32 v16, v2
	v_mov_b32_e32 v17, v2
	v_mov_b32_e32 v18, v2
	v_mov_b32_e32 v19, v2
	v_mov_b32_e32 v20, v2
	v_mov_b32_e32 v21, v2
	v_mov_b32_e32 v30, v2
	v_mov_b32_e32 v31, v2
	v_mov_b32_e32 v32, v2
	v_mov_b32_e32 v33, v2
	v_mov_b32_e32 v34, v2
	v_mov_b32_e32 v35, v2
	v_mov_b32_e32 v36, v2
	v_mov_b32_e32 v37, v2
	v_mov_b32_e32 v46, v2
	v_mov_b32_e32 v47, v2
	v_mov_b32_e32 v48, v2
	v_mov_b32_e32 v49, v2
	v_mov_b32_e32 v50, v2
	v_mov_b32_e32 v51, v2
	v_mov_b32_e32 v52, v2
	v_mov_b32_e32 v53, v2
	v_mov_b32_e32 v58, v2
	v_mov_b32_e32 v59, v2
	v_mov_b32_e32 v60, v2
	v_mov_b32_e32 v61, v2
	v_mov_b32_e32 v62, v2
	v_mov_b32_e32 v63, v2
	v_mov_b32_e32 v64, v2
	v_mov_b32_e32 v65, v2
	v_mov_b32_e32 v66, v2
	v_mov_b32_e32 v67, v2
	v_mov_b32_e32 v68, v2
	v_mov_b32_e32 v69, v2
	v_mov_b32_e32 v70, v2
	v_mov_b32_e32 v71, v2
	v_mov_b32_e32 v72, v2
	v_mov_b32_e32 v73, v2
	v_mov_b32_e32 v74, v2
	v_mov_b32_e32 v75, v2
	v_mov_b32_e32 v76, v2
	v_mov_b32_e32 v77, v2
	v_mov_b32_e32 v86, v2
	v_mov_b32_e32 v87, v2
	v_mov_b32_e32 v88, v2
	v_mov_b32_e32 v89, v2
	v_mov_b32_e32 v90, v2
	v_mov_b32_e32 v91, v2
	v_mov_b32_e32 v92, v2
	v_mov_b32_e32 v93, v2
	v_mov_b32_e32 v102, v2
	v_mov_b32_e32 v103, v2
	v_mov_b32_e32 v104, v2
	v_mov_b32_e32 v105, v2
	v_mov_b32_e32 v106, v2
	v_mov_b32_e32 v107, v2
	v_mov_b32_e32 v108, v2
	v_mov_b32_e32 v109, v2
	v_mov_b32_e32 v118, v2
	v_mov_b32_e32 v119, v2
	v_mov_b32_e32 v120, v2
	v_mov_b32_e32 v121, v2
	v_mov_b32_e32 v78, v2
	v_mov_b32_e32 v79, v2
	v_mov_b32_e32 v80, v2
	v_mov_b32_e32 v81, v2
	v_mov_b32_e32 v82, v2
	v_mov_b32_e32 v83, v2
	v_mov_b32_e32 v84, v2
	v_mov_b32_e32 v85, v2
	v_mov_b32_e32 v94, v2
	v_mov_b32_e32 v95, v2
	v_mov_b32_e32 v96, v2
	v_mov_b32_e32 v97, v2
	v_mov_b32_e32 v98, v2
	v_mov_b32_e32 v99, v2
	v_mov_b32_e32 v100, v2
	v_mov_b32_e32 v101, v2
	v_mov_b32_e32 v110, v2
	v_mov_b32_e32 v111, v2
	v_mov_b32_e32 v112, v2
	v_mov_b32_e32 v113, v2
	v_mov_b32_e32 v114, v2
	v_mov_b32_e32 v115, v2
	v_mov_b32_e32 v116, v2
	v_mov_b32_e32 v117, v2
	v_mov_b32_e32 v122, v2
	v_mov_b32_e32 v123, v2
	v_mov_b32_e32 v124, v2
	v_mov_b32_e32 v125, v2
	v_mov_b32_e32 v126, v2
	v_mov_b32_e32 v127, v2
	v_mov_b32_e32 v128, v2
	v_mov_b32_e32 v129, v2
	v_readfirstlane_b32 s32, v153
	s_nop 3
	s_lshr_b32 s32, s32, 6
	s_cmp_ge_u32 s32, 4
	s_cbranch_scc0 .Lgemm_prio_skip3
	s_setprio 1
.Lgemm_prio_skip3:
.LBB0_945:
	s_add_i32 s46, s22, 2
	s_add_u32 s47, s20, 0x80
	s_addc_u32 s23, s21, 0
	s_add_i32 s50, 0, 0x10000
	s_cmp_eq_u32 s38, s22
	s_cselect_b32 s23, s7, s23
	s_cselect_b32 s22, s6, s47
	v_add_u32_e32 v155, s50, v145
	s_cselect_b32 s49, s19, s45
	s_cselect_b32 s48, s18, s44
	s_add_i32 s47, 0, 0x14000
	ds_read_b128 v[136:139], v155
	ds_read_b128 v[140:143], v155 offset:1024
	ds_read_b128 v[148:151], v155 offset:2048
	ds_read_b128 v[156:159], v155 offset:3072
	v_add_u32_e32 v155, s47, v145
	ds_read_b128 v[160:163], v155
	ds_read_b128 v[164:167], v155 offset:1024
	ds_read_b128 v[168:171], v155 offset:2048
	ds_read_b128 v[172:175], v155 offset:3072
	v_lshl_add_u64 v[218:219], s[20:21], 0, v[132:133]
	s_add_i32 m0, s28, 0xc000
	ds_read_b128 v[176:179], v147
	ds_read_b128 v[180:183], v147 offset:1024
	ds_read_b128 v[184:187], v147 offset:2048
	ds_read_b128 v[188:191], v147 offset:3072
	ds_read_b128 v[192:195], v147 offset:4096
	ds_read_b128 v[196:199], v147 offset:5120
	ds_read_b128 v[206:209], v147 offset:6144
	ds_read_b128 v[210:213], v147 offset:7168
	global_load_lds_dwordx4 v[218:219], off
	v_lshl_add_u64 v[218:219], s[20:21], 0, v[134:135]
	s_add_i32 m0, s28, 0xe000
	s_nop 0
	global_load_lds_dwordx4 v[218:219], off
	s_waitcnt vmcnt(8)
	s_waitcnt lgkmcnt(0)
	s_barrier
; #define PG8_STAGE(bufoff, gbase, voff) do { _Pragma("unroll") for (int _i = 0; _i < 2; ++_i) \
;         __builtin_amdgcn_global_load_lds((const unsigned*)((const char*)(gbase) + (voff)[_i]), (LAS unsigned*)(lds + (bufoff) + ldsw + _i * 8192), 16, 0, 0); } while (0)
; #define PG8_LDA(dst, b, h) do { _Pragma("unroll") for (int m = 0; m < 4; ++m) _Pragma("unroll") for (int k = 0; k < 2; ++k) dst[m][k] = *(const LAS bf16x8*)(lds + PG8_SA(b, h) + aoff + m * 2048 + k * 1024); } while (0)
; #define PG8_MMA(ai, bj, At, Bt) do { __builtin_amdgcn_s_setprio(1); _Pragma("unroll") for (int m = 0; m < 4; ++m) _Pragma("unroll") for (int n = 0; n < 2; ++n) _Pragma("unroll") for (int k = 0; k < 2; ++k) \
;         acc[ai][bj][m][n] = __builtin_amdgcn_mfma_f32_16x16x32_bf16(Bt[n][k], At[m][k], acc[ai][bj][m][n], 0, 0, 0); __builtin_amdgcn_s_setprio(0); } while (0)
; #define PG8_WAIT_V(n) asm volatile("s_waitcnt vmcnt(" #n ")" ::: "memory")
; #define PG8_WAIT_L(n) asm volatile("s_waitcnt lgkmcnt(" #n ")" ::: "memory")
; #define PG8_BAR __builtin_amdgcn_s_barrier()
; #define PG8_SCHED __builtin_amdgcn_sched_barrier(0)
; template <class Epi>
; DI void gemm_phase(ldsp lds, const Gemm g, const StaticOrder S, const Epi E) {
;     ...
;             PG8_WAIT_V(8); PG8_WAIT_L(0); PG8_BAR; PG8_MMA(0, 0, At, B0); PG8_MMA(0, 1, At, B1); PG8_BAR; PG8_SCHED;
;             PG8_LDA(At, 0, 1); PG8_STAGE(PG8_SB(0, 0), b2, voffB); PG8_STAGE(PG8_SB(0, 1), b2 + hstepB, voffB); PG8_STAGE(PG8_SA(0, 0), a2, voffA);
;             PG8_WAIT_V(8); PG8_WAIT_L(0); PG8_BAR; PG8_MMA(1, 0, At, B0); PG8_MMA(1, 1, At, B1); PG8_BAR; PG8_SCHED;
	s_waitcnt lgkmcnt(0)
	v_mfma_f32_16x16x32_bf16 v[126:129], v[136:139], v[176:179], v[126:129]
	v_mfma_f32_16x16x32_bf16 v[122:125], v[148:151], v[176:179], v[122:125]
	v_mfma_f32_16x16x32_bf16 v[114:117], v[136:139], v[184:187], v[114:117]
	v_mfma_f32_16x16x32_bf16 v[110:113], v[148:151], v[184:187], v[110:113]
	v_mfma_f32_16x16x32_bf16 v[98:101], v[136:139], v[192:195], v[98:101]
	v_mfma_f32_16x16x32_bf16 v[94:97], v[148:151], v[192:195], v[94:97]
	v_mfma_f32_16x16x32_bf16 v[82:85], v[136:139], v[206:209], v[82:85]
	v_mfma_f32_16x16x32_bf16 v[78:81], v[148:151], v[206:209], v[78:81]
	v_mfma_f32_16x16x32_bf16 v[126:129], v[140:143], v[180:183], v[126:129]
	v_mfma_f32_16x16x32_bf16 v[122:125], v[156:159], v[180:183], v[122:125]
	v_mfma_f32_16x16x32_bf16 v[114:117], v[140:143], v[188:191], v[114:117]
	v_mfma_f32_16x16x32_bf16 v[110:113], v[156:159], v[188:191], v[110:113]
	v_mfma_f32_16x16x32_bf16 v[98:101], v[140:143], v[196:199], v[98:101]
	v_mfma_f32_16x16x32_bf16 v[94:97], v[156:159], v[196:199], v[94:97]
	v_mfma_f32_16x16x32_bf16 v[82:85], v[140:143], v[210:213], v[82:85]
	v_mfma_f32_16x16x32_bf16 v[78:81], v[156:159], v[210:213], v[78:81]
	v_mfma_f32_16x16x32_bf16 v[118:121], v[160:163], v[176:179], v[118:121]
	v_mfma_f32_16x16x32_bf16 v[106:109], v[168:171], v[176:179], v[106:109]
	v_mfma_f32_16x16x32_bf16 v[102:105], v[160:163], v[184:187], v[102:105]
	v_mfma_f32_16x16x32_bf16 v[90:93], v[168:171], v[184:187], v[90:93]
	v_mfma_f32_16x16x32_bf16 v[86:89], v[160:163], v[192:195], v[86:89]
	v_mfma_f32_16x16x32_bf16 v[74:77], v[168:171], v[192:195], v[74:77]
	v_mfma_f32_16x16x32_bf16 v[70:73], v[160:163], v[206:209], v[70:73]
	v_mfma_f32_16x16x32_bf16 v[66:69], v[168:171], v[206:209], v[66:69]
	v_mfma_f32_16x16x32_bf16 v[118:121], v[164:167], v[180:183], v[118:121]
	v_mfma_f32_16x16x32_bf16 v[106:109], v[172:175], v[180:183], v[106:109]
	v_mfma_f32_16x16x32_bf16 v[102:105], v[164:167], v[188:191], v[102:105]
	v_mfma_f32_16x16x32_bf16 v[90:93], v[172:175], v[188:191], v[90:93]
	v_mfma_f32_16x16x32_bf16 v[86:89], v[164:167], v[196:199], v[86:89]
	v_mfma_f32_16x16x32_bf16 v[74:77], v[172:175], v[196:199], v[74:77]
	v_mfma_f32_16x16x32_bf16 v[70:73], v[164:167], v[210:213], v[70:73]
	v_mfma_f32_16x16x32_bf16 v[66:69], v[172:175], v[210:213], v[66:69]
	s_barrier
	s_add_i32 s50, s50, s27
	v_lshl_add_u64 v[218:219], s[48:49], 0, v[0:1]
	s_mov_b32 m0, s50
	ds_read_b128 v[176:179], v147 offset:16384
	ds_read_b128 v[180:183], v147 offset:17408
	ds_read_b128 v[184:187], v147 offset:18432
	ds_read_b128 v[188:191], v147 offset:19456
	ds_read_b128 v[192:195], v147 offset:20480
	ds_read_b128 v[196:199], v147 offset:21504
	ds_read_b128 v[206:209], v147 offset:22528
	ds_read_b128 v[210:213], v147 offset:23552
	global_load_lds_dwordx4 v[218:219], off
	s_add_i32 m0, s50, 0x2000
	v_lshl_add_u64 v[220:221], s[48:49], 0, v[130:131]
	s_add_u32 s48, s48, s96
	s_addc_u32 s49, s49, 0
	s_add_i32 s47, s47, s27
	global_load_lds_dwordx4 v[220:221], off
	v_lshl_add_u64 v[222:223], s[48:49], 0, v[0:1]
	s_mov_b32 m0, s47
	v_lshl_add_u64 v[224:225], s[48:49], 0, v[130:131]
	global_load_lds_dwordx4 v[222:223], off
	s_add_i32 m0, s47, 0x2000
	v_lshl_add_u64 v[226:227], s[22:23], 0, v[0:1]
	global_load_lds_dwordx4 v[224:225], off
	s_mov_b32 m0, s28
	v_lshl_add_u64 v[228:229], s[22:23], 0, v[130:131]
	global_load_lds_dwordx4 v[226:227], off
	s_mov_b32 m0, s29
	s_nop 0
	global_load_lds_dwordx4 v[228:229], off
	s_waitcnt vmcnt(8)
	s_waitcnt lgkmcnt(0)
	s_barrier
	s_waitcnt lgkmcnt(0)
	v_mfma_f32_16x16x32_bf16 v[62:65], v[136:139], v[176:179], v[62:65]
	v_mfma_f32_16x16x32_bf16 v[58:61], v[148:151], v[176:179], v[58:61]
	v_mfma_f32_16x16x32_bf16 v[50:53], v[136:139], v[184:187], v[50:53]
	v_mfma_f32_16x16x32_bf16 v[46:49], v[148:151], v[184:187], v[46:49]
	v_mfma_f32_16x16x32_bf16 v[34:37], v[136:139], v[192:195], v[34:37]
	v_mfma_f32_16x16x32_bf16 v[30:33], v[148:151], v[192:195], v[30:33]
	v_mfma_f32_16x16x32_bf16 v[18:21], v[136:139], v[206:209], v[18:21]
	v_mfma_f32_16x16x32_bf16 v[14:17], v[148:151], v[206:209], v[14:17]
	v_mfma_f32_16x16x32_bf16 v[62:65], v[140:143], v[180:183], v[62:65]
	v_mfma_f32_16x16x32_bf16 v[58:61], v[156:159], v[180:183], v[58:61]
	v_mfma_f32_16x16x32_bf16 v[50:53], v[140:143], v[188:191], v[50:53]
	v_mfma_f32_16x16x32_bf16 v[46:49], v[156:159], v[188:191], v[46:49]
	v_mfma_f32_16x16x32_bf16 v[34:37], v[140:143], v[196:199], v[34:37]
	v_mfma_f32_16x16x32_bf16 v[30:33], v[156:159], v[196:199], v[30:33]
	v_mfma_f32_16x16x32_bf16 v[18:21], v[140:143], v[210:213], v[18:21]
	v_mfma_f32_16x16x32_bf16 v[14:17], v[156:159], v[210:213], v[14:17]
	v_mfma_f32_16x16x32_bf16 v[54:57], v[160:163], v[176:179], v[54:57]
	v_mfma_f32_16x16x32_bf16 v[42:45], v[168:171], v[176:179], v[42:45]
	v_mfma_f32_16x16x32_bf16 v[38:41], v[160:163], v[184:187], v[38:41]
	v_mfma_f32_16x16x32_bf16 v[26:29], v[168:171], v[184:187], v[26:29]
	v_mfma_f32_16x16x32_bf16 v[22:25], v[160:163], v[192:195], v[22:25]
	v_mfma_f32_16x16x32_bf16 v[10:13], v[168:171], v[192:195], v[10:13]
	v_mfma_f32_16x16x32_bf16 v[6:9], v[160:163], v[206:209], v[6:9]
	v_mfma_f32_16x16x32_bf16 v[2:5], v[168:171], v[206:209], v[2:5]
	v_mfma_f32_16x16x32_bf16 v[54:57], v[164:167], v[180:183], v[54:57]
	v_mfma_f32_16x16x32_bf16 v[42:45], v[172:175], v[180:183], v[42:45]
	v_mfma_f32_16x16x32_bf16 v[38:41], v[164:167], v[188:191], v[38:41]
	v_mfma_f32_16x16x32_bf16 v[26:29], v[172:175], v[188:191], v[26:29]
	v_mfma_f32_16x16x32_bf16 v[22:25], v[164:167], v[196:199], v[22:25]
	v_mfma_f32_16x16x32_bf16 v[10:13], v[172:175], v[196:199], v[10:13]
	v_mfma_f32_16x16x32_bf16 v[6:9], v[164:167], v[210:213], v[6:9]
	v_mfma_f32_16x16x32_bf16 v[2:5], v[172:175], v[210:213], v[2:5]
	s_barrier
; #define PG8_STAGE(bufoff, gbase, voff) do { _Pragma("unroll") for (int _i = 0; _i < 2; ++_i) \
;         __builtin_amdgcn_global_load_lds((const unsigned*)((const char*)(gbase) + (voff)[_i]), (LAS unsigned*)(lds + (bufoff) + ldsw + _i * 8192), 16, 0, 0); } while (0)
; #define PG8_LDA(dst, b, h) do { _Pragma("unroll") for (int m = 0; m < 4; ++m) _Pragma("unroll") for (int k = 0; k < 2; ++k) dst[m][k] = *(const LAS bf16x8*)(lds + PG8_SA(b, h) + aoff + m * 2048 + k * 1024); } while (0)
; #define PG8_LDB(dst, b, h) do { _Pragma("unroll") for (int n = 0; n < 2; ++n) _Pragma("unroll") for (int k = 0; k < 2; ++k) dst[n][k] = *(const LAS bf16x8*)(lds + PG8_SB(b, h) + boff + n * 2048 + k * 1024); } while (0)
; #define PG8_MMA(ai, bj, At, Bt) do { __builtin_amdgcn_s_setprio(1); _Pragma("unroll") for (int m = 0; m < 4; ++m) _Pragma("unroll") for (int n = 0; n < 2; ++n) _Pragma("unroll") for (int k = 0; k < 2; ++k) \
;         acc[ai][bj][m][n] = __builtin_amdgcn_mfma_f32_16x16x32_bf16(Bt[n][k], At[m][k], acc[ai][bj][m][n], 0, 0, 0); __builtin_amdgcn_s_setprio(0); } while (0)
; #define PG8_WAIT_V(n) asm volatile("s_waitcnt vmcnt(" #n ")" ::: "memory")
; #define PG8_WAIT_L(n) asm volatile("s_waitcnt lgkmcnt(" #n ")" ::: "memory")
; #define PG8_BAR __builtin_amdgcn_s_barrier()
; #define PG8_SCHED __builtin_amdgcn_sched_barrier(0)
; template <class Epi>
; DI void gemm_phase(ldsp lds, const Gemm g, const StaticOrder S, const Epi E) {
;     ...
;             PG8_LDB(B0, 1, 0); PG8_LDB(B1, 1, 1); PG8_SCHED; PG8_LDA(At, 1, 0); PG8_STAGE(PG8_SA(0, 1), a2 + hstepA, voffA);
;             PG8_WAIT_V(8); PG8_WAIT_L(0); PG8_BAR; PG8_MMA(0, 0, At, B0); PG8_MMA(0, 1, At, B1); PG8_BAR; PG8_SCHED;
	s_add_i32 s47, 0, 0x18000
	v_add_u32_e32 v155, s47, v145
	s_add_i32 s48, 0, 0x1c000
	ds_read_b128 v[136:139], v155
	ds_read_b128 v[140:143], v155 offset:1024
	ds_read_b128 v[148:151], v155 offset:2048
	ds_read_b128 v[156:159], v155 offset:3072
	v_add_u32_e32 v155, s48, v145
	ds_read_b128 v[160:163], v155
	ds_read_b128 v[164:167], v155 offset:1024
	ds_read_b128 v[168:171], v155 offset:2048
	ds_read_b128 v[172:175], v155 offset:3072
	s_add_u32 s22, s22, s96
	s_addc_u32 s23, s23, 0
	s_mov_b32 m0, s30
	v_lshl_add_u64 v[230:231], s[22:23], 0, v[0:1]
	ds_read_b128 v[176:179], v147 offset:32768
	ds_read_b128 v[180:183], v147 offset:33792
	ds_read_b128 v[184:187], v147 offset:34816
	ds_read_b128 v[188:191], v147 offset:35840
	ds_read_b128 v[192:195], v147 offset:36864
	ds_read_b128 v[196:199], v147 offset:37888
	ds_read_b128 v[206:209], v147 offset:38912
	ds_read_b128 v[210:213], v147 offset:39936
	global_load_lds_dwordx4 v[230:231], off
	v_lshl_add_u64 v[230:231], s[22:23], 0, v[130:131]
	s_mov_b32 m0, s31
	s_nop 0
	global_load_lds_dwordx4 v[230:231], off
	s_waitcnt vmcnt(8)
	s_waitcnt lgkmcnt(0)
	s_barrier
	s_waitcnt lgkmcnt(0)
	v_mfma_f32_16x16x32_bf16 v[126:129], v[136:139], v[176:179], v[126:129]
	v_mfma_f32_16x16x32_bf16 v[122:125], v[148:151], v[176:179], v[122:125]
	v_mfma_f32_16x16x32_bf16 v[114:117], v[136:139], v[184:187], v[114:117]
	v_mfma_f32_16x16x32_bf16 v[110:113], v[148:151], v[184:187], v[110:113]
	v_mfma_f32_16x16x32_bf16 v[98:101], v[136:139], v[192:195], v[98:101]
	v_mfma_f32_16x16x32_bf16 v[94:97], v[148:151], v[192:195], v[94:97]
	v_mfma_f32_16x16x32_bf16 v[82:85], v[136:139], v[206:209], v[82:85]
	v_mfma_f32_16x16x32_bf16 v[78:81], v[148:151], v[206:209], v[78:81]
	v_mfma_f32_16x16x32_bf16 v[126:129], v[140:143], v[180:183], v[126:129]
	v_mfma_f32_16x16x32_bf16 v[122:125], v[156:159], v[180:183], v[122:125]
	v_mfma_f32_16x16x32_bf16 v[114:117], v[140:143], v[188:191], v[114:117]
	v_mfma_f32_16x16x32_bf16 v[110:113], v[156:159], v[188:191], v[110:113]
	v_mfma_f32_16x16x32_bf16 v[98:101], v[140:143], v[196:199], v[98:101]
	v_mfma_f32_16x16x32_bf16 v[94:97], v[156:159], v[196:199], v[94:97]
	v_mfma_f32_16x16x32_bf16 v[82:85], v[140:143], v[210:213], v[82:85]
	v_mfma_f32_16x16x32_bf16 v[78:81], v[156:159], v[210:213], v[78:81]
	v_mfma_f32_16x16x32_bf16 v[118:121], v[160:163], v[176:179], v[118:121]
	v_mfma_f32_16x16x32_bf16 v[106:109], v[168:171], v[176:179], v[106:109]
	v_mfma_f32_16x16x32_bf16 v[102:105], v[160:163], v[184:187], v[102:105]
	v_mfma_f32_16x16x32_bf16 v[90:93], v[168:171], v[184:187], v[90:93]
	v_mfma_f32_16x16x32_bf16 v[86:89], v[160:163], v[192:195], v[86:89]
	v_mfma_f32_16x16x32_bf16 v[74:77], v[168:171], v[192:195], v[74:77]
	v_mfma_f32_16x16x32_bf16 v[70:73], v[160:163], v[206:209], v[70:73]
	v_mfma_f32_16x16x32_bf16 v[66:69], v[168:171], v[206:209], v[66:69]
	v_mfma_f32_16x16x32_bf16 v[118:121], v[164:167], v[180:183], v[118:121]
	v_mfma_f32_16x16x32_bf16 v[106:109], v[172:175], v[180:183], v[106:109]
	v_mfma_f32_16x16x32_bf16 v[102:105], v[164:167], v[188:191], v[102:105]
	v_mfma_f32_16x16x32_bf16 v[90:93], v[172:175], v[188:191], v[90:93]
	v_mfma_f32_16x16x32_bf16 v[86:89], v[164:167], v[196:199], v[86:89]
	v_mfma_f32_16x16x32_bf16 v[74:77], v[172:175], v[196:199], v[74:77]
	v_mfma_f32_16x16x32_bf16 v[70:73], v[164:167], v[210:213], v[70:73]
	v_mfma_f32_16x16x32_bf16 v[66:69], v[172:175], v[210:213], v[66:69]
	s_barrier
; #define PG8_STAGE(bufoff, gbase, voff) do { _Pragma("unroll") for (int _i = 0; _i < 2; ++_i) \
;         __builtin_amdgcn_global_load_lds((const unsigned*)((const char*)(gbase) + (voff)[_i]), (LAS unsigned*)(lds + (bufoff) + ldsw + _i * 8192), 16, 0, 0); } while (0)
; #define PG8_LDA(dst, b, h) do { _Pragma("unroll") for (int m = 0; m < 4; ++m) _Pragma("unroll") for (int k = 0; k < 2; ++k) dst[m][k] = *(const LAS bf16x8*)(lds + PG8_SA(b, h) + aoff + m * 2048 + k * 1024); } while (0)
; #define PG8_MMA(ai, bj, At, Bt) do { __builtin_amdgcn_s_setprio(1); _Pragma("unroll") for (int m = 0; m < 4; ++m) _Pragma("unroll") for (int n = 0; n < 2; ++n) _Pragma("unroll") for (int k = 0; k < 2; ++k) \
;         acc[ai][bj][m][n] = __builtin_amdgcn_mfma_f32_16x16x32_bf16(Bt[n][k], At[m][k], acc[ai][bj][m][n], 0, 0, 0); __builtin_amdgcn_s_setprio(0); } while (0)
; #define PG8_WAIT_V(n) asm volatile("s_waitcnt vmcnt(" #n ")" ::: "memory")
; #define PG8_WAIT_L(n) asm volatile("s_waitcnt lgkmcnt(" #n ")" ::: "memory")
; #define PG8_BAR __builtin_amdgcn_s_barrier()
; #define PG8_SCHED __builtin_amdgcn_sched_barrier(0)
; template <class Epi>
; DI void gemm_phase(ldsp lds, const Gemm g, const StaticOrder S, const Epi E) {
;     ...
;             PG8_LDA(At, 1, 1); PG8_STAGE(PG8_SB(1, 0), b3, voffB); PG8_STAGE(PG8_SB(1, 1), b3 + hstepB, voffB); PG8_STAGE(PG8_SA(1, 0), a3, voffA);
;             PG8_WAIT_V(8); PG8_WAIT_L(0); PG8_BAR; PG8_MMA(1, 0, At, B0); PG8_MMA(1, 1, At, B1); PG8_BAR; PG8_SCHED;
;         }
;         if (wr == 0) PG8_BAR;
	s_add_i32 s22, s47, s27
	v_lshl_add_u64 v[218:219], v[218:219], 0, s[88:89]
	s_mov_b32 m0, s22
	ds_read_b128 v[176:179], v147 offset:49152
	ds_read_b128 v[180:183], v147 offset:50176
	ds_read_b128 v[184:187], v147 offset:51200
	ds_read_b128 v[188:191], v147 offset:52224
	ds_read_b128 v[192:195], v147 offset:53248
	ds_read_b128 v[196:199], v147 offset:54272
	ds_read_b128 v[206:209], v147 offset:55296
	ds_read_b128 v[210:213], v147 offset:56320
	global_load_lds_dwordx4 v[218:219], off
	v_lshl_add_u64 v[218:219], v[220:221], 0, s[88:89]
	s_add_i32 m0, s22, 0x2000
	s_add_i32 s22, s48, s27
	global_load_lds_dwordx4 v[218:219], off
	v_lshl_add_u64 v[218:219], v[222:223], 0, s[88:89]
	s_mov_b32 m0, s22
	s_nop 0
	global_load_lds_dwordx4 v[218:219], off
	v_lshl_add_u64 v[218:219], v[224:225], 0, s[88:89]
	s_add_i32 m0, s22, 0x2000
	s_nop 0
	global_load_lds_dwordx4 v[218:219], off
	v_lshl_add_u64 v[218:219], v[226:227], 0, s[88:89]
	s_mov_b32 m0, s36
	s_nop 0
	global_load_lds_dwordx4 v[218:219], off
	v_lshl_add_u64 v[218:219], v[228:229], 0, s[88:89]
	s_mov_b32 m0, s37
	s_nop 0
	global_load_lds_dwordx4 v[218:219], off
	s_waitcnt vmcnt(8)
	s_waitcnt lgkmcnt(0)
	s_barrier
	s_waitcnt lgkmcnt(0)
	v_mfma_f32_16x16x32_bf16 v[62:65], v[136:139], v[176:179], v[62:65]
	v_mfma_f32_16x16x32_bf16 v[58:61], v[148:151], v[176:179], v[58:61]
	v_mfma_f32_16x16x32_bf16 v[50:53], v[136:139], v[184:187], v[50:53]
	v_mfma_f32_16x16x32_bf16 v[46:49], v[148:151], v[184:187], v[46:49]
	v_mfma_f32_16x16x32_bf16 v[34:37], v[136:139], v[192:195], v[34:37]
	v_mfma_f32_16x16x32_bf16 v[30:33], v[148:151], v[192:195], v[30:33]
	v_mfma_f32_16x16x32_bf16 v[18:21], v[136:139], v[206:209], v[18:21]
	v_mfma_f32_16x16x32_bf16 v[14:17], v[148:151], v[206:209], v[14:17]
	v_mfma_f32_16x16x32_bf16 v[62:65], v[140:143], v[180:183], v[62:65]
	v_mfma_f32_16x16x32_bf16 v[58:61], v[156:159], v[180:183], v[58:61]
	v_mfma_f32_16x16x32_bf16 v[50:53], v[140:143], v[188:191], v[50:53]
	v_mfma_f32_16x16x32_bf16 v[46:49], v[156:159], v[188:191], v[46:49]
	v_mfma_f32_16x16x32_bf16 v[34:37], v[140:143], v[196:199], v[34:37]
	v_mfma_f32_16x16x32_bf16 v[30:33], v[156:159], v[196:199], v[30:33]
	v_mfma_f32_16x16x32_bf16 v[18:21], v[140:143], v[210:213], v[18:21]
	v_mfma_f32_16x16x32_bf16 v[14:17], v[156:159], v[210:213], v[14:17]
	v_mfma_f32_16x16x32_bf16 v[54:57], v[160:163], v[176:179], v[54:57]
	v_mfma_f32_16x16x32_bf16 v[42:45], v[168:171], v[176:179], v[42:45]
	v_mfma_f32_16x16x32_bf16 v[38:41], v[160:163], v[184:187], v[38:41]
	v_mfma_f32_16x16x32_bf16 v[26:29], v[168:171], v[184:187], v[26:29]
	v_mfma_f32_16x16x32_bf16 v[22:25], v[160:163], v[192:195], v[22:25]
	v_mfma_f32_16x16x32_bf16 v[10:13], v[168:171], v[192:195], v[10:13]
	v_mfma_f32_16x16x32_bf16 v[6:9], v[160:163], v[206:209], v[6:9]
	v_mfma_f32_16x16x32_bf16 v[2:5], v[168:171], v[206:209], v[2:5]
	v_mfma_f32_16x16x32_bf16 v[54:57], v[164:167], v[180:183], v[54:57]
	v_mfma_f32_16x16x32_bf16 v[42:45], v[172:175], v[180:183], v[42:45]
	v_mfma_f32_16x16x32_bf16 v[38:41], v[164:167], v[188:191], v[38:41]
	v_mfma_f32_16x16x32_bf16 v[26:29], v[172:175], v[188:191], v[26:29]
	v_mfma_f32_16x16x32_bf16 v[22:25], v[164:167], v[196:199], v[22:25]
	v_mfma_f32_16x16x32_bf16 v[10:13], v[172:175], v[196:199], v[10:13]
	v_mfma_f32_16x16x32_bf16 v[6:9], v[164:167], v[210:213], v[6:9]
	v_mfma_f32_16x16x32_bf16 v[2:5], v[172:175], v[210:213], v[2:5]
	s_barrier
	s_add_u32 s20, s20, 0x100
	s_addc_u32 s21, s21, 0
	s_add_u32 s44, s44, 0x100
	s_addc_u32 s45, s45, 0
	s_cmp_ge_u32 s46, s35
	s_mov_b32 s22, s46
	s_cbranch_scc0 .LBB0_945
	s_setprio 0
	s_and_b64 vcc, exec, s[14:15]
	s_cbranch_vccz .LBB0_948
	s_barrier
